# gla_scan: state update of chunk n-1 issued inside the gate math of chunk n (one barrier per chunk, LDS/MFMA latency hidden), GA/GK share LDS write moved behind the gate math
# baseline (speedup 1.0000x reference)
;     ...
;     for (int u = vb; u < 256; u += nb) {
;         const int b = u >> 5, hh = (u >> 3) & 3, ksl = u & 7;
;         const int kc0 = hh * 128 + ksl * 16 + 2 * w;
;         float wa[2][16], bb[2];
; #pragma unroll
;         for (int e = 0; e < 2; ++e) { bb[e] = ba[kc0 + e];
; #pragma unroll
;             for (int jj = 0; jj < 16; ++jj) wa[e][jj] = w2[jj * 512 + kc0 + e]; }
;         f32x4 acc[2];
; #pragma unroll
;         for (int e = 0; e < 2; ++e) acc[e] = (f32x4){0.f, 0.f, 0.f, 0.f};
;         __syncthreads();
;         f32x4 a4n[4]; unsigned krawn; bf16x8 vfrn[2][2];
;         auto ldchunk = [&](int n) {
;             const int tok = b * 4096 + n * 64 + l;
; #pragma unroll
;             for (int q = 0; q < 4; ++q) a4n[q] = *(const f32x4*)(GA + (size_t)tok * 16 + 4 * q);
;             krawn = *(const unsigned*)(GK + (size_t)tok * 512 + kc0);
; #pragma unroll
;             for (int e = 0; e < 2; ++e)
; #pragma unroll
;                 for (int ks = 0; ks < 2; ++ks)
;                     vfrn[e][ks] = *(const bf16x8*)(GVT + ((size_t)(b * 1024 + hh * 256 + (2 * w + e) * 16 + (l & 15))) * 4096 + n * 64 + ks * 32 + (l >> 4) * 8);
;         };
;         ldchunk(0);
.LBB0_418:
	s_bfe_u32 s57, s56, 0x20003
	s_lshl_b32 s21, s56, 4
	s_and_b32 s21, s21, 0x70
	s_lshl_b32 s20, s57, 7
	s_or_b32 s20, s20, s21
	s_ashr_i32 s28, s56, 5
	v_mov_b32_e32 v220, 0xbfb8aa3b
	v_mov_b32_e32 v222, 1.0
	v_mov_b32_e32 v223, 1.0
	v_mov_b32_e32 v224, 0x3f317217
	v_mov_b32_e32 v225, 0x3f317217
	v_mov_b32_e32 v226, 0x3377d1cf
	v_mov_b32_e32 v227, 0x3377d1cf
	v_mov_b32_e32 v228, 0x3fb8aa3b
	v_mov_b32_e32 v229, 0x3fb8aa3b
	v_mov_b32_e32 v214, 0x3d800000
	v_mov_b32_e32 v215, 0x3d800000
	v_lshrrev_b32_e32 v27, 6, v249
	v_lshrrev_b32_e32 v61, 3, v160
	v_lshl_add_u32 v60, v27, 3, v61
	v_and_b32_e32 v62, 7, v160
	v_lshlrev_b32_e32 v230, 3, v160
	v_lshl_add_u32 v230, v27, 9, v230
	v_lshlrev_b32_e32 v231, 2, v62
	v_lshl_add_u32 v231, v60, 10, v231
	v_mul_u32_u24_e32 v28, 0x50, v60
	v_lshl_add_u32 v28, v62, 3, v28
	v_add_u32_e32 v28, 0x2010, v28
	v_mul_u32_u24_e32 v29, 0x50, v160
	v_add_u32_e32 v29, 0x2010, v29
	v_mul_u32_u24_e32 v30, 0x104, v62
	v_lshl_add_u32 v30, v60, 2, v30
	v_add_u32_e32 v30, 0x5010, v30
	v_mul_u32_u24_e32 v31, 0x104, v27
	v_lshl_add_u32 v31, v160, 2, v31
	v_add_u32_e32 v31, 0x5010, v31
	v_lshrrev_b32_e32 v64, 4, v160
	v_lshlrev_b32_e32 v232, 13, v72
	v_lshl_add_u32 v232, v64, 4, v232
	v_add_u32_e32 v233, 0x20000, v232
	v_lshlrev_b32_e32 v234, 8, v72
	v_lshl_add_u32 v234, v64, 3, v234
	v_add_u32_e32 v235, 0x1000, v234
	v_add_u32_e32 v65, s20, v161
	v_lshlrev_b32_e32 v65, 2, v65
	s_mov_b64 s[50:51], s[8:9]
	global_load_dwordx2 v[86:87], v65, s[50:51]
	global_load_dwordx2 v[88:89], v65, s[50:51] offset:2048
	s_add_u32 s50, s50, 0x1000
	s_addc_u32 s51, s51, 0
	global_load_dwordx2 v[90:91], v65, s[50:51]
	global_load_dwordx2 v[92:93], v65, s[50:51] offset:2048
	s_add_u32 s50, s50, 0x1000
	s_addc_u32 s51, s51, 0
	global_load_dwordx2 v[94:95], v65, s[50:51]
	global_load_dwordx2 v[96:97], v65, s[50:51] offset:2048
	s_add_u32 s50, s50, 0x1000
	s_addc_u32 s51, s51, 0
	global_load_dwordx2 v[98:99], v65, s[50:51]
	global_load_dwordx2 v[100:101], v65, s[50:51] offset:2048
	s_add_u32 s50, s50, 0x1000
	s_addc_u32 s51, s51, 0
	global_load_dwordx2 v[102:103], v65, s[50:51]
	global_load_dwordx2 v[104:105], v65, s[50:51] offset:2048
	s_add_u32 s50, s50, 0x1000
	s_addc_u32 s51, s51, 0
	global_load_dwordx2 v[106:107], v65, s[50:51]
	global_load_dwordx2 v[108:109], v65, s[50:51] offset:2048
	s_add_u32 s50, s50, 0x1000
	s_addc_u32 s51, s51, 0
	global_load_dwordx2 v[110:111], v65, s[50:51]
	global_load_dwordx2 v[112:113], v65, s[50:51] offset:2048
	s_add_u32 s50, s50, 0x1000
	s_addc_u32 s51, s51, 0
	global_load_dwordx2 v[114:115], v65, s[50:51]
	global_load_dwordx2 v[116:117], v65, s[50:51] offset:2048
	s_add_u32 s50, s50, 0x1000
	s_addc_u32 s51, s51, 0
	global_load_dwordx2 v[118:119], v65, s[18:19]
	v_readlane_b32 s26, v253, 13
	v_readlane_b32 s27, v253, 14
	v_readlane_b32 s58, v254, 26
	v_readlane_b32 s59, v254, 27
	v_readlane_b32 s34, v253, 11
	v_readlane_b32 s35, v253, 12
	v_readlane_b32 s100, v254, 28
	v_readlane_b32 s101, v254, 29
	s_lshl_b32 s52, s28, 18
	s_add_u32 s26, s26, s52
	s_addc_u32 s27, s27, 0
	s_lshl_b32 s52, s28, 22
	s_lshl_b32 s53, s20, 1
	s_add_u32 s52, s52, s53
	s_add_u32 s58, s58, s52
	s_addc_u32 s59, s59, 0
	s_lshl_b32 s52, s28, 23
	s_lshl_b32 s53, s57, 21
	s_add_u32 s52, s52, s53
	s_add_u32 s34, s34, s52
	s_addc_u32 s35, s35, 0
	s_lshl_b32 s52, s28, 8
	s_or_b32 s52, s52, s57
	s_lshl_b32 s52, s52, 16
	s_lshl_b32 s53, s21, 1
	s_add_u32 s52, s52, s53
	s_add_u32 s100, s100, s52
	s_addc_u32 s101, s101, 0
	v_mov_b32_e32 v0, 0
	v_mov_b32_e32 v1, 0
	v_mov_b32_e32 v2, 0
	v_mov_b32_e32 v3, 0
	v_mov_b32_e32 v4, 0
	v_mov_b32_e32 v5, 0
	v_mov_b32_e32 v6, 0
	v_mov_b32_e32 v7, 0
	s_barrier
	global_load_dwordx2 v[48:49], v230, s[26:27]
	global_load_dword v50, v231, s[58:59]
	s_add_u32 s26, s26, 0x1000
	s_addc_u32 s27, s27, 0
	s_add_u32 s58, s58, 0x10000
	s_addc_u32 s59, s59, 0
	global_load_dwordx2 v[52:53], v230, s[26:27]
	global_load_dword v54, v231, s[58:59]
	s_add_u32 s26, s26, 0x1000
	s_addc_u32 s27, s27, 0
	s_add_u32 s58, s58, 0x10000
	s_addc_u32 s59, s59, 0
	global_load_dwordx2 v[56:57], v230, s[26:27]
	global_load_dword v58, v231, s[58:59]
	s_add_u32 s26, s26, 0x1000
	s_addc_u32 s27, s27, 0
	s_add_u32 s58, s58, 0x10000
	s_addc_u32 s59, s59, 0
	global_load_dwordx4 v[32:35], v232, s[34:35]
	global_load_dwordx4 v[36:39], v232, s[34:35] offset:64
	global_load_dwordx4 v[40:43], v233, s[34:35]
	global_load_dwordx4 v[44:47], v233, s[34:35] offset:64
	s_add_u32 s34, s34, 0x80
	s_addc_u32 s35, s35, 0
	s_waitcnt vmcnt(0)
	ds_write_b64 v28, v[48:49] offset:0
	ds_write_b32 v30, v50 offset:0
	s_waitcnt lgkmcnt(0)
	s_barrier
; DI bf16_t f2bf(float x) { return (bf16_t)(pk2(x, 0.f) & 0xffffu); }
; DI float bf2f(unsigned x) { return __uint_as_float(x << 16); }
;     ...
;         for (int n = 0; n < 64; ++n) {
;             const int buf = n & 1;
;             f32x4 a4[4]; bf16x8 vfr[2][2];
; #pragma unroll
;             for (int q = 0; q < 4; ++q) a4[q] = a4n[q];
;             const unsigned kraw = krawn;
; #pragma unroll
;             for (int e = 0; e < 2; ++e)
; #pragma unroll
;                 for (int ks = 0; ks < 2; ++ks) vfr[e][ks] = vfrn[e][ks];
;             if (n + 1 < 64) ldchunk(n + 1);
;             float cum[2];
; #pragma unroll
;             for (int e = 0; e < 2; ++e) {
;                 float z = bb[e];
; #pragma unroll
;                 for (int q = 0; q < 4; ++q) { z += a4[q].x * wa[e][4 * q] + a4[q].y * wa[e][4 * q + 1] + a4[q].z * wa[e][4 * q + 2] + a4[q].w * wa[e][4 * q + 3]; }
;                 cum[e] = (fminf(z, 0.f) - __logf(1.f + __expf(-fabsf(z)))) * (1.f / 16.f);
;             }
; #pragma unroll
;             for (int o = 1; o < 64; o <<= 1) {
;                 const float t0 = __shfl_up(cum[0], o), t1 = __shfl_up(cum[1], o);
;                 if (l >= o) { cum[0] += t0; cum[1] += t1; }
;             }
;             const float tot0 = __shfl(cum[0], 63), tot1 = __shfl(cum[1], 63);
;             kdl[(buf * 16 + 2 * w) * 64 + l] = f2bf(bf2f(kraw & 0xffffu) * __expf(tot0 - cum[0]));
;             kdl[(buf * 16 + 2 * w + 1) * 64 + l] = f2bf(bf2f(kraw >> 16) * __expf(tot1 - cum[1]));
;             if (l == 0) { decl[buf * 16 + 2 * w] = __expf(tot0); decl[buf * 16 + 2 * w + 1] = __expf(tot1); }
;             __syncthreads();
	ds_read_b128 v[8:11], v29 offset:0
	ds_read_b128 v[12:15], v29 offset:16
	ds_read_b128 v[16:19], v29 offset:32
	ds_read_b128 v[20:23], v29 offset:48
	ds_read_b32 v24, v31 offset:0
	global_load_dwordx2 v[48:49], v230, s[26:27]
	global_load_dword v50, v231, s[58:59]
	s_add_u32 s26, s26, 0x1000
	s_addc_u32 s27, s27, 0
	s_add_u32 s58, s58, 0x10000
	s_addc_u32 s59, s59, 0
	global_load_dwordx4 v[178:181], v232, s[34:35]
	global_load_dwordx4 v[182:185], v232, s[34:35] offset:64
	global_load_dwordx4 v[186:189], v233, s[34:35]
	global_load_dwordx4 v[190:193], v233, s[34:35] offset:64
	s_add_u32 s34, s34, 0x80
	s_addc_u32 s35, s35, 0
	s_waitcnt lgkmcnt(0)
	v_pk_fma_f32 v[64:65], v[8:9], v[86:87], v[118:119] op_sel:[0,0,0] op_sel_hi:[0,1,1]
	v_pk_mul_f32 v[66:67], v[16:17], v[102:103] op_sel:[0,0] op_sel_hi:[0,1]
	v_pk_fma_f32 v[64:65], v[8:9], v[88:89], v[64:65] op_sel:[1,0,0] op_sel_hi:[1,1,1]
	v_pk_fma_f32 v[66:67], v[16:17], v[104:105], v[66:67] op_sel:[1,0,0] op_sel_hi:[1,1,1]
	v_pk_fma_f32 v[64:65], v[10:11], v[90:91], v[64:65] op_sel:[0,0,0] op_sel_hi:[0,1,1]
	v_pk_fma_f32 v[66:67], v[18:19], v[106:107], v[66:67] op_sel:[0,0,0] op_sel_hi:[0,1,1]
	v_pk_fma_f32 v[64:65], v[10:11], v[92:93], v[64:65] op_sel:[1,0,0] op_sel_hi:[1,1,1]
	v_pk_fma_f32 v[66:67], v[18:19], v[108:109], v[66:67] op_sel:[1,0,0] op_sel_hi:[1,1,1]
	v_pk_fma_f32 v[64:65], v[12:13], v[94:95], v[64:65] op_sel:[0,0,0] op_sel_hi:[0,1,1]
	v_pk_fma_f32 v[66:67], v[20:21], v[110:111], v[66:67] op_sel:[0,0,0] op_sel_hi:[0,1,1]
	v_pk_fma_f32 v[64:65], v[12:13], v[96:97], v[64:65] op_sel:[1,0,0] op_sel_hi:[1,1,1]
	v_pk_fma_f32 v[66:67], v[20:21], v[112:113], v[66:67] op_sel:[1,0,0] op_sel_hi:[1,1,1]
	v_pk_fma_f32 v[64:65], v[14:15], v[98:99], v[64:65] op_sel:[0,0,0] op_sel_hi:[0,1,1]
	v_pk_fma_f32 v[66:67], v[22:23], v[114:115], v[66:67] op_sel:[0,0,0] op_sel_hi:[0,1,1]
	v_pk_fma_f32 v[64:65], v[14:15], v[100:101], v[64:65] op_sel:[1,0,0] op_sel_hi:[1,1,1]
	v_pk_fma_f32 v[66:67], v[22:23], v[116:117], v[66:67] op_sel:[1,0,0] op_sel_hi:[1,1,1]
	v_lshlrev_b32_e32 v148, 16, v24
	v_pk_add_f32 v[64:65], v[64:65], v[66:67]
	v_and_b32_e32 v149, 0xffff0000, v24
	v_mul_f32_e64 v68, |v64|, v220
	v_mul_f32_e64 v69, |v65|, v220
	v_exp_f32_e32 v68, v68
	v_exp_f32_e32 v69, v69
	v_min_f32_e32 v70, 0, v64
	v_min_f32_e32 v71, 0, v65
	v_pk_add_f32 v[68:69], v[68:69], v[222:223]
	s_nop 0
	v_log_f32_e32 v138, v68
	v_log_f32_e32 v139, v69
	s_nop 0
	v_pk_mul_f32 v[140:141], v[138:139], v[224:225]
	s_nop 0
	v_pk_fma_f32 v[142:143], v[138:139], v[224:225], v[140:141] neg_lo:[0,0,1] neg_hi:[0,0,1]
	s_nop 0
	v_pk_fma_f32 v[142:143], v[138:139], v[226:227], v[142:143]
	s_nop 0
	v_pk_fma_f32 v[142:143], v[138:139], v[224:225], v[142:143]
	s_nop 0
	v_pk_add_f32 v[144:145], v[70:71], v[142:143] neg_lo:[0,1] neg_hi:[0,1]
	s_nop 0
	v_pk_mul_f32 v[144:145], v[144:145], v[214:215]
	s_nop 1
	v_add_f32_dpp v144, v144, v144 row_shr:1 row_mask:0xf bank_mask:0xf
	v_add_f32_dpp v145, v145, v145 row_shr:1 row_mask:0xf bank_mask:0xf
	s_nop 0
	v_add_f32_dpp v144, v144, v144 row_shr:2 row_mask:0xf bank_mask:0xf
	v_add_f32_dpp v145, v145, v145 row_shr:2 row_mask:0xf bank_mask:0xf
	s_nop 0
	v_add_f32_dpp v144, v144, v144 row_shr:4 row_mask:0xf bank_mask:0xf
	v_add_f32_dpp v145, v145, v145 row_shr:4 row_mask:0xf bank_mask:0xf
	s_nop 0
	v_add_f32_dpp v144, v144, v144 row_shr:8 row_mask:0xf bank_mask:0xf
	v_add_f32_dpp v145, v145, v145 row_shr:8 row_mask:0xf bank_mask:0xf
	s_nop 0
	v_add_f32_dpp v144, v144, v144 row_bcast:15 row_mask:0xa bank_mask:0xf
	v_add_f32_dpp v145, v145, v145 row_bcast:15 row_mask:0xa bank_mask:0xf
	s_nop 0
	v_add_f32_dpp v144, v144, v144 row_bcast:31 row_mask:0xc bank_mask:0xf
	v_add_f32_dpp v145, v145, v145 row_bcast:31 row_mask:0xc bank_mask:0xf
	s_nop 0
	v_readlane_b32 s98, v144, 63
	v_readlane_b32 s99, v145, 63
	s_nop 1
	v_pk_add_f32 v[146:147], s[98:99], v[144:145] neg_lo:[0,1] neg_hi:[0,1]
	v_mul_f32_e64 v152, s98, v228
	v_mul_f32_e64 v153, s99, v228
	v_pk_mul_f32 v[146:147], v[146:147], v[228:229]
	v_exp_f32_e32 v152, v152
	v_exp_f32_e32 v153, v153
	v_exp_f32_e32 v146, v146
	v_exp_f32_e32 v147, v147
	s_nop 0
	v_pk_mul_f32 v[146:147], v[146:147], v[148:149]
	s_nop 0
	v_cvt_pk_bf16_f32 v150, v146, v147
	s_nop 0
	ds_write_b16 v172, v150 offset:0
	ds_write_b16_d16_hi v172, v150 offset:128
	s_and_saveexec_b64 s[20:21], vcc
	ds_write_b64 v163, v[152:153] offset:4096
	s_mov_b64 exec, s[20:21]
	s_waitcnt vmcnt(22)
	ds_write_b64 v28, v[52:53] offset:5120
	ds_write_b32 v30, v54 offset:2080
	s_waitcnt lgkmcnt(0)
	s_barrier
; #define MFMA16(a, b, c) __builtin_amdgcn_mfma_f32_16x16x32_bf16((a), (b), (c), 0, 0, 0)
;     ...
;         for (int n = 0; n < 64; ++n) {
;             const int buf = n & 1;
;             f32x4 a4[4]; bf16x8 vfr[2][2];
; #pragma unroll
;             for (int q = 0; q < 4; ++q) a4[q] = a4n[q];
;             const unsigned kraw = krawn;
; #pragma unroll
;             for (int e = 0; e < 2; ++e)
; #pragma unroll
;                 for (int ks = 0; ks < 2; ++ks) vfr[e][ks] = vfrn[e][ks];
;             if (n + 1 < 64) ldchunk(n + 1);
;             float cum[2];
; #pragma unroll
;             for (int e = 0; e < 2; ++e) {
;                 float z = bb[e];
; #pragma unroll
;                 for (int q = 0; q < 4; ++q) { z += a4[q].x * wa[e][4 * q] + a4[q].y * wa[e][4 * q + 1] + a4[q].z * wa[e][4 * q + 2] + a4[q].w * wa[e][4 * q + 3]; }
;                 cum[e] = (fminf(z, 0.f) - __logf(1.f + __expf(-fabsf(z)))) * (1.f / 16.f);
;             }
; #pragma unroll
;             for (int o = 1; o < 64; o <<= 1) {
;                 const float t0 = __shfl_up(cum[0], o), t1 = __shfl_up(cum[1], o);
;                 if (l >= o) { cum[0] += t0; cum[1] += t1; }
;             }
;             const float tot0 = __shfl(cum[0], 63), tot1 = __shfl(cum[1], 63);
;             kdl[(buf * 16 + 2 * w) * 64 + l] = f2bf(bf2f(kraw & 0xffffu) * __expf(tot0 - cum[0]));
;             kdl[(buf * 16 + 2 * w + 1) * 64 + l] = f2bf(bf2f(kraw >> 16) * __expf(tot1 - cum[1]));
;             if (l == 0) { decl[buf * 16 + 2 * w] = __expf(tot0); decl[buf * 16 + 2 * w + 1] = __expf(tot1); }
;             __syncthreads();
;             const f32x4 d4 = *(const f32x4*)(decl + buf * 16 + (l >> 4) * 4);
; #pragma unroll
;             for (int e = 0; e < 2; ++e) acc[e] = acc[e] * d4;
; #pragma unroll
;             for (int ks = 0; ks < 2; ++ks) {
;                 const bf16x8 af = *(const bf16x8*)(kdl + (buf * 16 + (l & 15)) * 64 + ks * 32 + (l >> 4) * 8);
; #pragma unroll
;                 for (int e = 0; e < 2; ++e) acc[e] = MFMA16(af, vfr[e][ks], acc[e]);
;             }
;             const int cidx = b * 64 + n;
; #pragma unroll
;             for (int e = 0; e < 2; ++e) {
;                 const int vv = (2 * w + e) * 16 + (l & 15);
;                 *(u32x2*)(ST + (((size_t)(cidx * 4 + hh)) * 256 + vv) * 128 + ksl * 16 + (l >> 4) * 4) = pk4(acc[e].x, acc[e].y, acc[e].z, acc[e].w);
;             }
	ds_read_b128 v[8:11], v29 offset:5120
	ds_read_b128 v[12:15], v29 offset:5136
	ds_read_b128 v[16:19], v29 offset:5152
	ds_read_b128 v[20:23], v29 offset:5168
	ds_read_b32 v24, v31 offset:2080
	global_load_dwordx2 v[52:53], v230, s[26:27]
	global_load_dword v54, v231, s[58:59]
	s_add_u32 s26, s26, 0x1000
	s_addc_u32 s27, s27, 0
	s_add_u32 s58, s58, 0x10000
	s_addc_u32 s59, s59, 0
	global_load_dwordx4 v[194:197], v232, s[34:35]
	global_load_dwordx4 v[198:201], v232, s[34:35] offset:64
	global_load_dwordx4 v[202:205], v233, s[34:35]
	global_load_dwordx4 v[206:209], v233, s[34:35] offset:64
	s_add_u32 s34, s34, 0x80
	s_addc_u32 s35, s35, 0
	ds_read_b128 v[154:157], v75 offset:0
	ds_read_b128 v[240:243], v164 offset:4096
	ds_read_b128 v[236:239], v75 offset:64
	s_waitcnt lgkmcnt(3)
	v_pk_fma_f32 v[64:65], v[8:9], v[86:87], v[118:119] op_sel:[0,0,0] op_sel_hi:[0,1,1]
	v_pk_mul_f32 v[66:67], v[16:17], v[102:103] op_sel:[0,0] op_sel_hi:[0,1]
	v_pk_fma_f32 v[64:65], v[8:9], v[88:89], v[64:65] op_sel:[1,0,0] op_sel_hi:[1,1,1]
	v_pk_fma_f32 v[66:67], v[16:17], v[104:105], v[66:67] op_sel:[1,0,0] op_sel_hi:[1,1,1]
	v_pk_fma_f32 v[64:65], v[10:11], v[90:91], v[64:65] op_sel:[0,0,0] op_sel_hi:[0,1,1]
	v_pk_fma_f32 v[66:67], v[18:19], v[106:107], v[66:67] op_sel:[0,0,0] op_sel_hi:[0,1,1]
	v_pk_fma_f32 v[64:65], v[10:11], v[92:93], v[64:65] op_sel:[1,0,0] op_sel_hi:[1,1,1]
	v_pk_fma_f32 v[66:67], v[18:19], v[108:109], v[66:67] op_sel:[1,0,0] op_sel_hi:[1,1,1]
	v_pk_fma_f32 v[64:65], v[12:13], v[94:95], v[64:65] op_sel:[0,0,0] op_sel_hi:[0,1,1]
	v_pk_fma_f32 v[66:67], v[20:21], v[110:111], v[66:67] op_sel:[0,0,0] op_sel_hi:[0,1,1]
	v_pk_fma_f32 v[64:65], v[12:13], v[96:97], v[64:65] op_sel:[1,0,0] op_sel_hi:[1,1,1]
	v_pk_fma_f32 v[66:67], v[20:21], v[112:113], v[66:67] op_sel:[1,0,0] op_sel_hi:[1,1,1]
	v_pk_fma_f32 v[64:65], v[14:15], v[98:99], v[64:65] op_sel:[0,0,0] op_sel_hi:[0,1,1]
	v_pk_fma_f32 v[66:67], v[22:23], v[114:115], v[66:67] op_sel:[0,0,0] op_sel_hi:[0,1,1]
	v_pk_fma_f32 v[64:65], v[14:15], v[100:101], v[64:65] op_sel:[1,0,0] op_sel_hi:[1,1,1]
	v_pk_fma_f32 v[66:67], v[22:23], v[116:117], v[66:67] op_sel:[1,0,0] op_sel_hi:[1,1,1]
	v_lshlrev_b32_e32 v148, 16, v24
	v_pk_add_f32 v[64:65], v[64:65], v[66:67]
	v_and_b32_e32 v149, 0xffff0000, v24
	s_waitcnt lgkmcnt(0)
	v_pk_mul_f32 v[0:1], v[0:1], v[240:241]
	v_pk_mul_f32 v[2:3], v[2:3], v[242:243]
	v_pk_mul_f32 v[4:5], v[4:5], v[240:241]
	v_pk_mul_f32 v[6:7], v[6:7], v[242:243]
	s_waitcnt vmcnt(16)
	s_nop 0
	v_mfma_f32_16x16x32_bf16 v[0:3], v[154:157], v[32:35], v[0:3]
	v_mfma_f32_16x16x32_bf16 v[4:7], v[154:157], v[40:43], v[4:7]
	v_mfma_f32_16x16x32_bf16 v[0:3], v[236:239], v[36:39], v[0:3]
	v_mfma_f32_16x16x32_bf16 v[4:7], v[236:239], v[44:47], v[4:7]
	v_mul_f32_e64 v68, |v64|, v220
	v_mul_f32_e64 v69, |v65|, v220
	v_exp_f32_e32 v68, v68
	v_exp_f32_e32 v69, v69
	v_min_f32_e32 v70, 0, v64
	v_min_f32_e32 v71, 0, v65
	v_pk_add_f32 v[68:69], v[68:69], v[222:223]
	s_nop 0
	v_log_f32_e32 v138, v68
	v_log_f32_e32 v139, v69
	s_nop 0
	v_pk_mul_f32 v[140:141], v[138:139], v[224:225]
	s_nop 0
	v_pk_fma_f32 v[142:143], v[138:139], v[224:225], v[140:141] neg_lo:[0,0,1] neg_hi:[0,0,1]
	s_nop 0
	v_pk_fma_f32 v[142:143], v[138:139], v[226:227], v[142:143]
	s_nop 0
	v_pk_fma_f32 v[142:143], v[138:139], v[224:225], v[142:143]
	s_nop 0
	v_pk_add_f32 v[144:145], v[70:71], v[142:143] neg_lo:[0,1] neg_hi:[0,1]
	s_nop 0
	v_pk_mul_f32 v[144:145], v[144:145], v[214:215]
	v_cvt_pk_bf16_f32 v244, v0, v1
	v_cvt_pk_bf16_f32 v245, v2, v3
	v_cvt_pk_bf16_f32 v246, v4, v5
	v_cvt_pk_bf16_f32 v247, v6, v7
	global_store_dwordx2 v234, v[244:245], s[100:101]
	global_store_dwordx2 v235, v[246:247], s[100:101]
	s_add_u32 s100, s100, 0x40000
	s_addc_u32 s101, s101, 0
	v_add_f32_dpp v144, v144, v144 row_shr:1 row_mask:0xf bank_mask:0xf
	v_add_f32_dpp v145, v145, v145 row_shr:1 row_mask:0xf bank_mask:0xf
	s_nop 0
	v_add_f32_dpp v144, v144, v144 row_shr:2 row_mask:0xf bank_mask:0xf
	v_add_f32_dpp v145, v145, v145 row_shr:2 row_mask:0xf bank_mask:0xf
	s_nop 0
	v_add_f32_dpp v144, v144, v144 row_shr:4 row_mask:0xf bank_mask:0xf
	v_add_f32_dpp v145, v145, v145 row_shr:4 row_mask:0xf bank_mask:0xf
	s_nop 0
	v_add_f32_dpp v144, v144, v144 row_shr:8 row_mask:0xf bank_mask:0xf
	v_add_f32_dpp v145, v145, v145 row_shr:8 row_mask:0xf bank_mask:0xf
	s_nop 0
	v_add_f32_dpp v144, v144, v144 row_bcast:15 row_mask:0xa bank_mask:0xf
	v_add_f32_dpp v145, v145, v145 row_bcast:15 row_mask:0xa bank_mask:0xf
	s_nop 0
	v_add_f32_dpp v144, v144, v144 row_bcast:31 row_mask:0xc bank_mask:0xf
	v_add_f32_dpp v145, v145, v145 row_bcast:31 row_mask:0xc bank_mask:0xf
	s_nop 0
	v_readlane_b32 s98, v144, 63
	v_readlane_b32 s99, v145, 63
	s_nop 1
	v_pk_add_f32 v[146:147], s[98:99], v[144:145] neg_lo:[0,1] neg_hi:[0,1]
	v_mul_f32_e64 v152, s98, v228
	v_mul_f32_e64 v153, s99, v228
	v_pk_mul_f32 v[146:147], v[146:147], v[228:229]
	v_exp_f32_e32 v152, v152
	v_exp_f32_e32 v153, v153
	v_exp_f32_e32 v146, v146
	v_exp_f32_e32 v147, v147
	s_nop 0
	v_pk_mul_f32 v[146:147], v[146:147], v[148:149]
	s_nop 0
	v_cvt_pk_bf16_f32 v150, v146, v147
	s_nop 0
	ds_write_b16 v172, v150 offset:2048
	ds_write_b16_d16_hi v172, v150 offset:2176
	s_and_saveexec_b64 s[20:21], vcc
	ds_write_b64 v163, v[152:153] offset:4160
	s_mov_b64 exec, s[20:21]
	s_waitcnt vmcnt(22)
	ds_write_b64 v28, v[56:57] offset:0
	ds_write_b32 v30, v58 offset:0
	s_waitcnt lgkmcnt(0)
	s_barrier
; #define MFMA16(a, b, c) __builtin_amdgcn_mfma_f32_16x16x32_bf16((a), (b), (c), 0, 0, 0)
;     ...
;         for (int n = 0; n < 64; ++n) {
;             const int buf = n & 1;
;             f32x4 a4[4]; bf16x8 vfr[2][2];
; #pragma unroll
;             for (int q = 0; q < 4; ++q) a4[q] = a4n[q];
;             const unsigned kraw = krawn;
; #pragma unroll
;             for (int e = 0; e < 2; ++e)
; #pragma unroll
;                 for (int ks = 0; ks < 2; ++ks) vfr[e][ks] = vfrn[e][ks];
;             if (n + 1 < 64) ldchunk(n + 1);
;             float cum[2];
; #pragma unroll
;             for (int e = 0; e < 2; ++e) {
;                 float z = bb[e];
; #pragma unroll
;                 for (int q = 0; q < 4; ++q) { z += a4[q].x * wa[e][4 * q] + a4[q].y * wa[e][4 * q + 1] + a4[q].z * wa[e][4 * q + 2] + a4[q].w * wa[e][4 * q + 3]; }
;                 cum[e] = (fminf(z, 0.f) - __logf(1.f + __expf(-fabsf(z)))) * (1.f / 16.f);
;             }
; #pragma unroll
;             for (int o = 1; o < 64; o <<= 1) {
;                 const float t0 = __shfl_up(cum[0], o), t1 = __shfl_up(cum[1], o);
;                 if (l >= o) { cum[0] += t0; cum[1] += t1; }
;             }
;             const float tot0 = __shfl(cum[0], 63), tot1 = __shfl(cum[1], 63);
;             kdl[(buf * 16 + 2 * w) * 64 + l] = f2bf(bf2f(kraw & 0xffffu) * __expf(tot0 - cum[0]));
;             kdl[(buf * 16 + 2 * w + 1) * 64 + l] = f2bf(bf2f(kraw >> 16) * __expf(tot1 - cum[1]));
;             if (l == 0) { decl[buf * 16 + 2 * w] = __expf(tot0); decl[buf * 16 + 2 * w + 1] = __expf(tot1); }
;             __syncthreads();
;             const f32x4 d4 = *(const f32x4*)(decl + buf * 16 + (l >> 4) * 4);
; #pragma unroll
;             for (int e = 0; e < 2; ++e) acc[e] = acc[e] * d4;
; #pragma unroll
;             for (int ks = 0; ks < 2; ++ks) {
;                 const bf16x8 af = *(const bf16x8*)(kdl + (buf * 16 + (l & 15)) * 64 + ks * 32 + (l >> 4) * 8);
; #pragma unroll
;                 for (int e = 0; e < 2; ++e) acc[e] = MFMA16(af, vfr[e][ks], acc[e]);
;             }
;             const int cidx = b * 64 + n;
; #pragma unroll
;             for (int e = 0; e < 2; ++e) {
;                 const int vv = (2 * w + e) * 16 + (l & 15);
;                 *(u32x2*)(ST + (((size_t)(cidx * 4 + hh)) * 256 + vv) * 128 + ksl * 16 + (l >> 4) * 4) = pk4(acc[e].x, acc[e].y, acc[e].z, acc[e].w);
;             }
	ds_read_b128 v[8:11], v29 offset:0
	ds_read_b128 v[12:15], v29 offset:16
	ds_read_b128 v[16:19], v29 offset:32
	ds_read_b128 v[20:23], v29 offset:48
	ds_read_b32 v24, v31 offset:0
	global_load_dwordx2 v[56:57], v230, s[26:27]
	global_load_dword v58, v231, s[58:59]
	s_add_u32 s26, s26, 0x1000
	s_addc_u32 s27, s27, 0
	s_add_u32 s58, s58, 0x10000
	s_addc_u32 s59, s59, 0
	global_load_dwordx4 v[32:35], v232, s[34:35]
	global_load_dwordx4 v[36:39], v232, s[34:35] offset:64
	global_load_dwordx4 v[40:43], v233, s[34:35]
	global_load_dwordx4 v[44:47], v233, s[34:35] offset:64
	s_add_u32 s34, s34, 0x80
	s_addc_u32 s35, s35, 0
	ds_read_b128 v[154:157], v75 offset:2048
	ds_read_b128 v[240:243], v164 offset:4160
	ds_read_b128 v[236:239], v75 offset:2112
	s_waitcnt lgkmcnt(3)
	v_pk_fma_f32 v[64:65], v[8:9], v[86:87], v[118:119] op_sel:[0,0,0] op_sel_hi:[0,1,1]
	v_pk_mul_f32 v[66:67], v[16:17], v[102:103] op_sel:[0,0] op_sel_hi:[0,1]
	v_pk_fma_f32 v[64:65], v[8:9], v[88:89], v[64:65] op_sel:[1,0,0] op_sel_hi:[1,1,1]
	v_pk_fma_f32 v[66:67], v[16:17], v[104:105], v[66:67] op_sel:[1,0,0] op_sel_hi:[1,1,1]
	v_pk_fma_f32 v[64:65], v[10:11], v[90:91], v[64:65] op_sel:[0,0,0] op_sel_hi:[0,1,1]
	v_pk_fma_f32 v[66:67], v[18:19], v[106:107], v[66:67] op_sel:[0,0,0] op_sel_hi:[0,1,1]
	v_pk_fma_f32 v[64:65], v[10:11], v[92:93], v[64:65] op_sel:[1,0,0] op_sel_hi:[1,1,1]
	v_pk_fma_f32 v[66:67], v[18:19], v[108:109], v[66:67] op_sel:[1,0,0] op_sel_hi:[1,1,1]
	v_pk_fma_f32 v[64:65], v[12:13], v[94:95], v[64:65] op_sel:[0,0,0] op_sel_hi:[0,1,1]
	v_pk_fma_f32 v[66:67], v[20:21], v[110:111], v[66:67] op_sel:[0,0,0] op_sel_hi:[0,1,1]
	v_pk_fma_f32 v[64:65], v[12:13], v[96:97], v[64:65] op_sel:[1,0,0] op_sel_hi:[1,1,1]
	v_pk_fma_f32 v[66:67], v[20:21], v[112:113], v[66:67] op_sel:[1,0,0] op_sel_hi:[1,1,1]
	v_pk_fma_f32 v[64:65], v[14:15], v[98:99], v[64:65] op_sel:[0,0,0] op_sel_hi:[0,1,1]
	v_pk_fma_f32 v[66:67], v[22:23], v[114:115], v[66:67] op_sel:[0,0,0] op_sel_hi:[0,1,1]
	v_pk_fma_f32 v[64:65], v[14:15], v[100:101], v[64:65] op_sel:[1,0,0] op_sel_hi:[1,1,1]
	v_pk_fma_f32 v[66:67], v[22:23], v[116:117], v[66:67] op_sel:[1,0,0] op_sel_hi:[1,1,1]
	v_lshlrev_b32_e32 v148, 16, v24
	v_pk_add_f32 v[64:65], v[64:65], v[66:67]
	v_and_b32_e32 v149, 0xffff0000, v24
	s_waitcnt lgkmcnt(0)
	v_pk_mul_f32 v[0:1], v[0:1], v[240:241]
	v_pk_mul_f32 v[2:3], v[2:3], v[242:243]
	v_pk_mul_f32 v[4:5], v[4:5], v[240:241]
	v_pk_mul_f32 v[6:7], v[6:7], v[242:243]
	s_waitcnt vmcnt(14)
	s_nop 0
	v_mfma_f32_16x16x32_bf16 v[0:3], v[154:157], v[178:181], v[0:3]
	v_mfma_f32_16x16x32_bf16 v[4:7], v[154:157], v[186:189], v[4:7]
	v_mfma_f32_16x16x32_bf16 v[0:3], v[236:239], v[182:185], v[0:3]
	v_mfma_f32_16x16x32_bf16 v[4:7], v[236:239], v[190:193], v[4:7]
	v_mul_f32_e64 v68, |v64|, v220
	v_mul_f32_e64 v69, |v65|, v220
	v_exp_f32_e32 v68, v68
	v_exp_f32_e32 v69, v69
	v_min_f32_e32 v70, 0, v64
	v_min_f32_e32 v71, 0, v65
	v_pk_add_f32 v[68:69], v[68:69], v[222:223]
	s_nop 0
	v_log_f32_e32 v138, v68
	v_log_f32_e32 v139, v69
	s_nop 0
	v_pk_mul_f32 v[140:141], v[138:139], v[224:225]
	s_nop 0
	v_pk_fma_f32 v[142:143], v[138:139], v[224:225], v[140:141] neg_lo:[0,0,1] neg_hi:[0,0,1]
	s_nop 0
	v_pk_fma_f32 v[142:143], v[138:139], v[226:227], v[142:143]
	s_nop 0
	v_pk_fma_f32 v[142:143], v[138:139], v[224:225], v[142:143]
	s_nop 0
	v_pk_add_f32 v[144:145], v[70:71], v[142:143] neg_lo:[0,1] neg_hi:[0,1]
	s_nop 0
	v_pk_mul_f32 v[144:145], v[144:145], v[214:215]
	v_cvt_pk_bf16_f32 v244, v0, v1
	v_cvt_pk_bf16_f32 v245, v2, v3
	v_cvt_pk_bf16_f32 v246, v4, v5
	v_cvt_pk_bf16_f32 v247, v6, v7
	global_store_dwordx2 v234, v[244:245], s[100:101]
	global_store_dwordx2 v235, v[246:247], s[100:101]
	s_add_u32 s100, s100, 0x40000
	s_addc_u32 s101, s101, 0
	v_add_f32_dpp v144, v144, v144 row_shr:1 row_mask:0xf bank_mask:0xf
	v_add_f32_dpp v145, v145, v145 row_shr:1 row_mask:0xf bank_mask:0xf
	s_nop 0
	v_add_f32_dpp v144, v144, v144 row_shr:2 row_mask:0xf bank_mask:0xf
	v_add_f32_dpp v145, v145, v145 row_shr:2 row_mask:0xf bank_mask:0xf
	s_nop 0
	v_add_f32_dpp v144, v144, v144 row_shr:4 row_mask:0xf bank_mask:0xf
	v_add_f32_dpp v145, v145, v145 row_shr:4 row_mask:0xf bank_mask:0xf
	s_nop 0
	v_add_f32_dpp v144, v144, v144 row_shr:8 row_mask:0xf bank_mask:0xf
	v_add_f32_dpp v145, v145, v145 row_shr:8 row_mask:0xf bank_mask:0xf
	s_nop 0
	v_add_f32_dpp v144, v144, v144 row_bcast:15 row_mask:0xa bank_mask:0xf
	v_add_f32_dpp v145, v145, v145 row_bcast:15 row_mask:0xa bank_mask:0xf
	s_nop 0
	v_add_f32_dpp v144, v144, v144 row_bcast:31 row_mask:0xc bank_mask:0xf
	v_add_f32_dpp v145, v145, v145 row_bcast:31 row_mask:0xc bank_mask:0xf
	s_nop 0
	v_readlane_b32 s98, v144, 63
	v_readlane_b32 s99, v145, 63
	s_nop 1
	v_pk_add_f32 v[146:147], s[98:99], v[144:145] neg_lo:[0,1] neg_hi:[0,1]
	v_mul_f32_e64 v152, s98, v228
	v_mul_f32_e64 v153, s99, v228
	v_pk_mul_f32 v[146:147], v[146:147], v[228:229]
	v_exp_f32_e32 v152, v152
	v_exp_f32_e32 v153, v153
	v_exp_f32_e32 v146, v146
	v_exp_f32_e32 v147, v147
	s_nop 0
	v_pk_mul_f32 v[146:147], v[146:147], v[148:149]
	s_nop 0
	v_cvt_pk_bf16_f32 v150, v146, v147
	s_nop 0
	ds_write_b16 v172, v150 offset:0
	ds_write_b16_d16_hi v172, v150 offset:128
	s_and_saveexec_b64 s[20:21], vcc
	ds_write_b64 v163, v[152:153] offset:4096
	s_mov_b64 exec, s[20:21]
	s_waitcnt vmcnt(20)
	ds_write_b64 v28, v[48:49] offset:5120
	ds_write_b32 v30, v50 offset:2080
	s_waitcnt lgkmcnt(0)
	s_barrier
; #define MFMA16(a, b, c) __builtin_amdgcn_mfma_f32_16x16x32_bf16((a), (b), (c), 0, 0, 0)
;     ...
;         for (int n = 0; n < 64; ++n) {
;             const int buf = n & 1;
;             f32x4 a4[4]; bf16x8 vfr[2][2];
; #pragma unroll
;             for (int q = 0; q < 4; ++q) a4[q] = a4n[q];
;             const unsigned kraw = krawn;
; #pragma unroll
;             for (int e = 0; e < 2; ++e)
; #pragma unroll
;                 for (int ks = 0; ks < 2; ++ks) vfr[e][ks] = vfrn[e][ks];
;             if (n + 1 < 64) ldchunk(n + 1);
;             float cum[2];
; #pragma unroll
;             for (int e = 0; e < 2; ++e) {
;                 float z = bb[e];
; #pragma unroll
;                 for (int q = 0; q < 4; ++q) { z += a4[q].x * wa[e][4 * q] + a4[q].y * wa[e][4 * q + 1] + a4[q].z * wa[e][4 * q + 2] + a4[q].w * wa[e][4 * q + 3]; }
;                 cum[e] = (fminf(z, 0.f) - __logf(1.f + __expf(-fabsf(z)))) * (1.f / 16.f);
;             }
; #pragma unroll
;             for (int o = 1; o < 64; o <<= 1) {
;                 const float t0 = __shfl_up(cum[0], o), t1 = __shfl_up(cum[1], o);
;                 if (l >= o) { cum[0] += t0; cum[1] += t1; }
;             }
;             const float tot0 = __shfl(cum[0], 63), tot1 = __shfl(cum[1], 63);
;             kdl[(buf * 16 + 2 * w) * 64 + l] = f2bf(bf2f(kraw & 0xffffu) * __expf(tot0 - cum[0]));
;             kdl[(buf * 16 + 2 * w + 1) * 64 + l] = f2bf(bf2f(kraw >> 16) * __expf(tot1 - cum[1]));
;             if (l == 0) { decl[buf * 16 + 2 * w] = __expf(tot0); decl[buf * 16 + 2 * w + 1] = __expf(tot1); }
;             __syncthreads();
;             const f32x4 d4 = *(const f32x4*)(decl + buf * 16 + (l >> 4) * 4);
; #pragma unroll
;             for (int e = 0; e < 2; ++e) acc[e] = acc[e] * d4;
; #pragma unroll
;             for (int ks = 0; ks < 2; ++ks) {
;                 const bf16x8 af = *(const bf16x8*)(kdl + (buf * 16 + (l & 15)) * 64 + ks * 32 + (l >> 4) * 8);
; #pragma unroll
;                 for (int e = 0; e < 2; ++e) acc[e] = MFMA16(af, vfr[e][ks], acc[e]);
;             }
;             const int cidx = b * 64 + n;
; #pragma unroll
;             for (int e = 0; e < 2; ++e) {
;                 const int vv = (2 * w + e) * 16 + (l & 15);
;                 *(u32x2*)(ST + (((size_t)(cidx * 4 + hh)) * 256 + vv) * 128 + ksl * 16 + (l >> 4) * 4) = pk4(acc[e].x, acc[e].y, acc[e].z, acc[e].w);
;             }
	ds_read_b128 v[8:11], v29 offset:5120
	ds_read_b128 v[12:15], v29 offset:5136
	ds_read_b128 v[16:19], v29 offset:5152
	ds_read_b128 v[20:23], v29 offset:5168
	ds_read_b32 v24, v31 offset:2080
	global_load_dwordx2 v[48:49], v230, s[26:27]
	global_load_dword v50, v231, s[58:59]
	s_add_u32 s26, s26, 0x1000
	s_addc_u32 s27, s27, 0
	s_add_u32 s58, s58, 0x10000
	s_addc_u32 s59, s59, 0
	global_load_dwordx4 v[178:181], v232, s[34:35]
	global_load_dwordx4 v[182:185], v232, s[34:35] offset:64
	global_load_dwordx4 v[186:189], v233, s[34:35]
	global_load_dwordx4 v[190:193], v233, s[34:35] offset:64
	s_add_u32 s34, s34, 0x80
	s_addc_u32 s35, s35, 0
	ds_read_b128 v[154:157], v75 offset:0
	ds_read_b128 v[240:243], v164 offset:4096
	ds_read_b128 v[236:239], v75 offset:64
	s_waitcnt lgkmcnt(3)
	v_pk_fma_f32 v[64:65], v[8:9], v[86:87], v[118:119] op_sel:[0,0,0] op_sel_hi:[0,1,1]
	v_pk_mul_f32 v[66:67], v[16:17], v[102:103] op_sel:[0,0] op_sel_hi:[0,1]
	v_pk_fma_f32 v[64:65], v[8:9], v[88:89], v[64:65] op_sel:[1,0,0] op_sel_hi:[1,1,1]
	v_pk_fma_f32 v[66:67], v[16:17], v[104:105], v[66:67] op_sel:[1,0,0] op_sel_hi:[1,1,1]
	v_pk_fma_f32 v[64:65], v[10:11], v[90:91], v[64:65] op_sel:[0,0,0] op_sel_hi:[0,1,1]
	v_pk_fma_f32 v[66:67], v[18:19], v[106:107], v[66:67] op_sel:[0,0,0] op_sel_hi:[0,1,1]
	v_pk_fma_f32 v[64:65], v[10:11], v[92:93], v[64:65] op_sel:[1,0,0] op_sel_hi:[1,1,1]
	v_pk_fma_f32 v[66:67], v[18:19], v[108:109], v[66:67] op_sel:[1,0,0] op_sel_hi:[1,1,1]
	v_pk_fma_f32 v[64:65], v[12:13], v[94:95], v[64:65] op_sel:[0,0,0] op_sel_hi:[0,1,1]
	v_pk_fma_f32 v[66:67], v[20:21], v[110:111], v[66:67] op_sel:[0,0,0] op_sel_hi:[0,1,1]
	v_pk_fma_f32 v[64:65], v[12:13], v[96:97], v[64:65] op_sel:[1,0,0] op_sel_hi:[1,1,1]
	v_pk_fma_f32 v[66:67], v[20:21], v[112:113], v[66:67] op_sel:[1,0,0] op_sel_hi:[1,1,1]
	v_pk_fma_f32 v[64:65], v[14:15], v[98:99], v[64:65] op_sel:[0,0,0] op_sel_hi:[0,1,1]
	v_pk_fma_f32 v[66:67], v[22:23], v[114:115], v[66:67] op_sel:[0,0,0] op_sel_hi:[0,1,1]
	v_pk_fma_f32 v[64:65], v[14:15], v[100:101], v[64:65] op_sel:[1,0,0] op_sel_hi:[1,1,1]
	v_pk_fma_f32 v[66:67], v[22:23], v[116:117], v[66:67] op_sel:[1,0,0] op_sel_hi:[1,1,1]
	v_lshlrev_b32_e32 v148, 16, v24
	v_pk_add_f32 v[64:65], v[64:65], v[66:67]
	v_and_b32_e32 v149, 0xffff0000, v24
	s_waitcnt lgkmcnt(0)
	v_pk_mul_f32 v[0:1], v[0:1], v[240:241]
	v_pk_mul_f32 v[2:3], v[2:3], v[242:243]
	v_pk_mul_f32 v[4:5], v[4:5], v[240:241]
	v_pk_mul_f32 v[6:7], v[6:7], v[242:243]
	s_waitcnt vmcnt(16)
	s_nop 0
	v_mfma_f32_16x16x32_bf16 v[0:3], v[154:157], v[194:197], v[0:3]
	v_mfma_f32_16x16x32_bf16 v[4:7], v[154:157], v[202:205], v[4:7]
	v_mfma_f32_16x16x32_bf16 v[0:3], v[236:239], v[198:201], v[0:3]
	v_mfma_f32_16x16x32_bf16 v[4:7], v[236:239], v[206:209], v[4:7]
	v_mul_f32_e64 v68, |v64|, v220
	v_mul_f32_e64 v69, |v65|, v220
	v_exp_f32_e32 v68, v68
	v_exp_f32_e32 v69, v69
	v_min_f32_e32 v70, 0, v64
	v_min_f32_e32 v71, 0, v65
	v_pk_add_f32 v[68:69], v[68:69], v[222:223]
	s_nop 0
	v_log_f32_e32 v138, v68
	v_log_f32_e32 v139, v69
	s_nop 0
	v_pk_mul_f32 v[140:141], v[138:139], v[224:225]
	s_nop 0
	v_pk_fma_f32 v[142:143], v[138:139], v[224:225], v[140:141] neg_lo:[0,0,1] neg_hi:[0,0,1]
	s_nop 0
	v_pk_fma_f32 v[142:143], v[138:139], v[226:227], v[142:143]
	s_nop 0
	v_pk_fma_f32 v[142:143], v[138:139], v[224:225], v[142:143]
	s_nop 0
	v_pk_add_f32 v[144:145], v[70:71], v[142:143] neg_lo:[0,1] neg_hi:[0,1]
	s_nop 0
	v_pk_mul_f32 v[144:145], v[144:145], v[214:215]
	v_cvt_pk_bf16_f32 v244, v0, v1
	v_cvt_pk_bf16_f32 v245, v2, v3
	v_cvt_pk_bf16_f32 v246, v4, v5
	v_cvt_pk_bf16_f32 v247, v6, v7
	global_store_dwordx2 v234, v[244:245], s[100:101]
	global_store_dwordx2 v235, v[246:247], s[100:101]
	s_add_u32 s100, s100, 0x40000
	s_addc_u32 s101, s101, 0
	v_add_f32_dpp v144, v144, v144 row_shr:1 row_mask:0xf bank_mask:0xf
	v_add_f32_dpp v145, v145, v145 row_shr:1 row_mask:0xf bank_mask:0xf
	s_nop 0
	v_add_f32_dpp v144, v144, v144 row_shr:2 row_mask:0xf bank_mask:0xf
	v_add_f32_dpp v145, v145, v145 row_shr:2 row_mask:0xf bank_mask:0xf
	s_nop 0
	v_add_f32_dpp v144, v144, v144 row_shr:4 row_mask:0xf bank_mask:0xf
	v_add_f32_dpp v145, v145, v145 row_shr:4 row_mask:0xf bank_mask:0xf
	s_nop 0
	v_add_f32_dpp v144, v144, v144 row_shr:8 row_mask:0xf bank_mask:0xf
	v_add_f32_dpp v145, v145, v145 row_shr:8 row_mask:0xf bank_mask:0xf
	s_nop 0
	v_add_f32_dpp v144, v144, v144 row_bcast:15 row_mask:0xa bank_mask:0xf
	v_add_f32_dpp v145, v145, v145 row_bcast:15 row_mask:0xa bank_mask:0xf
	s_nop 0
	v_add_f32_dpp v144, v144, v144 row_bcast:31 row_mask:0xc bank_mask:0xf
	v_add_f32_dpp v145, v145, v145 row_bcast:31 row_mask:0xc bank_mask:0xf
	s_nop 0
	v_readlane_b32 s98, v144, 63
	v_readlane_b32 s99, v145, 63
	s_nop 1
	v_pk_add_f32 v[146:147], s[98:99], v[144:145] neg_lo:[0,1] neg_hi:[0,1]
	v_mul_f32_e64 v152, s98, v228
	v_mul_f32_e64 v153, s99, v228
	v_pk_mul_f32 v[146:147], v[146:147], v[228:229]
	v_exp_f32_e32 v152, v152
	v_exp_f32_e32 v153, v153
	v_exp_f32_e32 v146, v146
	v_exp_f32_e32 v147, v147
	s_nop 0
	v_pk_mul_f32 v[146:147], v[146:147], v[148:149]
	s_nop 0
	v_cvt_pk_bf16_f32 v150, v146, v147
	s_nop 0
	ds_write_b16 v172, v150 offset:2048
	ds_write_b16_d16_hi v172, v150 offset:2176
	s_and_saveexec_b64 s[20:21], vcc
	ds_write_b64 v163, v[152:153] offset:4160
	s_mov_b64 exec, s[20:21]
	s_waitcnt vmcnt(22)
	ds_write_b64 v28, v[52:53] offset:0
	ds_write_b32 v30, v54 offset:0
	s_waitcnt lgkmcnt(0)
	s_barrier
; #define MFMA16(a, b, c) __builtin_amdgcn_mfma_f32_16x16x32_bf16((a), (b), (c), 0, 0, 0)
;     ...
;         for (int n = 0; n < 64; ++n) {
;             const int buf = n & 1;
;             f32x4 a4[4]; bf16x8 vfr[2][2];
; #pragma unroll
;             for (int q = 0; q < 4; ++q) a4[q] = a4n[q];
;             const unsigned kraw = krawn;
; #pragma unroll
;             for (int e = 0; e < 2; ++e)
; #pragma unroll
;                 for (int ks = 0; ks < 2; ++ks) vfr[e][ks] = vfrn[e][ks];
;             if (n + 1 < 64) ldchunk(n + 1);
;             float cum[2];
; #pragma unroll
;             for (int e = 0; e < 2; ++e) {
;                 float z = bb[e];
; #pragma unroll
;                 for (int q = 0; q < 4; ++q) { z += a4[q].x * wa[e][4 * q] + a4[q].y * wa[e][4 * q + 1] + a4[q].z * wa[e][4 * q + 2] + a4[q].w * wa[e][4 * q + 3]; }
;                 cum[e] = (fminf(z, 0.f) - __logf(1.f + __expf(-fabsf(z)))) * (1.f / 16.f);
;             }
; #pragma unroll
;             for (int o = 1; o < 64; o <<= 1) {
;                 const float t0 = __shfl_up(cum[0], o), t1 = __shfl_up(cum[1], o);
;                 if (l >= o) { cum[0] += t0; cum[1] += t1; }
;             }
;             const float tot0 = __shfl(cum[0], 63), tot1 = __shfl(cum[1], 63);
;             kdl[(buf * 16 + 2 * w) * 64 + l] = f2bf(bf2f(kraw & 0xffffu) * __expf(tot0 - cum[0]));
;             kdl[(buf * 16 + 2 * w + 1) * 64 + l] = f2bf(bf2f(kraw >> 16) * __expf(tot1 - cum[1]));
;             if (l == 0) { decl[buf * 16 + 2 * w] = __expf(tot0); decl[buf * 16 + 2 * w + 1] = __expf(tot1); }
;             __syncthreads();
;             const f32x4 d4 = *(const f32x4*)(decl + buf * 16 + (l >> 4) * 4);
; #pragma unroll
;             for (int e = 0; e < 2; ++e) acc[e] = acc[e] * d4;
; #pragma unroll
;             for (int ks = 0; ks < 2; ++ks) {
;                 const bf16x8 af = *(const bf16x8*)(kdl + (buf * 16 + (l & 15)) * 64 + ks * 32 + (l >> 4) * 8);
; #pragma unroll
;                 for (int e = 0; e < 2; ++e) acc[e] = MFMA16(af, vfr[e][ks], acc[e]);
;             }
;             const int cidx = b * 64 + n;
; #pragma unroll
;             for (int e = 0; e < 2; ++e) {
;                 const int vv = (2 * w + e) * 16 + (l & 15);
;                 *(u32x2*)(ST + (((size_t)(cidx * 4 + hh)) * 256 + vv) * 128 + ksl * 16 + (l >> 4) * 4) = pk4(acc[e].x, acc[e].y, acc[e].z, acc[e].w);
;             }
	ds_read_b128 v[8:11], v29 offset:0
	ds_read_b128 v[12:15], v29 offset:16
	ds_read_b128 v[16:19], v29 offset:32
	ds_read_b128 v[20:23], v29 offset:48
	ds_read_b32 v24, v31 offset:0
	global_load_dwordx2 v[52:53], v230, s[26:27]
	global_load_dword v54, v231, s[58:59]
	s_add_u32 s26, s26, 0x1000
	s_addc_u32 s27, s27, 0
	s_add_u32 s58, s58, 0x10000
	s_addc_u32 s59, s59, 0
	global_load_dwordx4 v[194:197], v232, s[34:35]
	global_load_dwordx4 v[198:201], v232, s[34:35] offset:64
	global_load_dwordx4 v[202:205], v233, s[34:35]
	global_load_dwordx4 v[206:209], v233, s[34:35] offset:64
	s_add_u32 s34, s34, 0x80
	s_addc_u32 s35, s35, 0
	ds_read_b128 v[154:157], v75 offset:2048
	ds_read_b128 v[240:243], v164 offset:4160
	ds_read_b128 v[236:239], v75 offset:2112
	s_waitcnt lgkmcnt(3)
	v_pk_fma_f32 v[64:65], v[8:9], v[86:87], v[118:119] op_sel:[0,0,0] op_sel_hi:[0,1,1]
	v_pk_mul_f32 v[66:67], v[16:17], v[102:103] op_sel:[0,0] op_sel_hi:[0,1]
	v_pk_fma_f32 v[64:65], v[8:9], v[88:89], v[64:65] op_sel:[1,0,0] op_sel_hi:[1,1,1]
	v_pk_fma_f32 v[66:67], v[16:17], v[104:105], v[66:67] op_sel:[1,0,0] op_sel_hi:[1,1,1]
	v_pk_fma_f32 v[64:65], v[10:11], v[90:91], v[64:65] op_sel:[0,0,0] op_sel_hi:[0,1,1]
	v_pk_fma_f32 v[66:67], v[18:19], v[106:107], v[66:67] op_sel:[0,0,0] op_sel_hi:[0,1,1]
	v_pk_fma_f32 v[64:65], v[10:11], v[92:93], v[64:65] op_sel:[1,0,0] op_sel_hi:[1,1,1]
	v_pk_fma_f32 v[66:67], v[18:19], v[108:109], v[66:67] op_sel:[1,0,0] op_sel_hi:[1,1,1]
	v_pk_fma_f32 v[64:65], v[12:13], v[94:95], v[64:65] op_sel:[0,0,0] op_sel_hi:[0,1,1]
	v_pk_fma_f32 v[66:67], v[20:21], v[110:111], v[66:67] op_sel:[0,0,0] op_sel_hi:[0,1,1]
	v_pk_fma_f32 v[64:65], v[12:13], v[96:97], v[64:65] op_sel:[1,0,0] op_sel_hi:[1,1,1]
	v_pk_fma_f32 v[66:67], v[20:21], v[112:113], v[66:67] op_sel:[1,0,0] op_sel_hi:[1,1,1]
	v_pk_fma_f32 v[64:65], v[14:15], v[98:99], v[64:65] op_sel:[0,0,0] op_sel_hi:[0,1,1]
	v_pk_fma_f32 v[66:67], v[22:23], v[114:115], v[66:67] op_sel:[0,0,0] op_sel_hi:[0,1,1]
	v_pk_fma_f32 v[64:65], v[14:15], v[100:101], v[64:65] op_sel:[1,0,0] op_sel_hi:[1,1,1]
	v_pk_fma_f32 v[66:67], v[22:23], v[116:117], v[66:67] op_sel:[1,0,0] op_sel_hi:[1,1,1]
	v_lshlrev_b32_e32 v148, 16, v24
	v_pk_add_f32 v[64:65], v[64:65], v[66:67]
	v_and_b32_e32 v149, 0xffff0000, v24
	s_waitcnt lgkmcnt(0)
	v_pk_mul_f32 v[0:1], v[0:1], v[240:241]
	v_pk_mul_f32 v[2:3], v[2:3], v[242:243]
	v_pk_mul_f32 v[4:5], v[4:5], v[240:241]
	v_pk_mul_f32 v[6:7], v[6:7], v[242:243]
	s_waitcnt vmcnt(16)
	s_nop 0
	v_mfma_f32_16x16x32_bf16 v[0:3], v[154:157], v[32:35], v[0:3]
	v_mfma_f32_16x16x32_bf16 v[4:7], v[154:157], v[40:43], v[4:7]
	v_mfma_f32_16x16x32_bf16 v[0:3], v[236:239], v[36:39], v[0:3]
	v_mfma_f32_16x16x32_bf16 v[4:7], v[236:239], v[44:47], v[4:7]
	v_mul_f32_e64 v68, |v64|, v220
	v_mul_f32_e64 v69, |v65|, v220
	v_exp_f32_e32 v68, v68
	v_exp_f32_e32 v69, v69
	v_min_f32_e32 v70, 0, v64
	v_min_f32_e32 v71, 0, v65
	v_pk_add_f32 v[68:69], v[68:69], v[222:223]
	s_nop 0
	v_log_f32_e32 v138, v68
	v_log_f32_e32 v139, v69
	s_nop 0
	v_pk_mul_f32 v[140:141], v[138:139], v[224:225]
	s_nop 0
	v_pk_fma_f32 v[142:143], v[138:139], v[224:225], v[140:141] neg_lo:[0,0,1] neg_hi:[0,0,1]
	s_nop 0
	v_pk_fma_f32 v[142:143], v[138:139], v[226:227], v[142:143]
	s_nop 0
	v_pk_fma_f32 v[142:143], v[138:139], v[224:225], v[142:143]
	s_nop 0
	v_pk_add_f32 v[144:145], v[70:71], v[142:143] neg_lo:[0,1] neg_hi:[0,1]
	s_nop 0
	v_pk_mul_f32 v[144:145], v[144:145], v[214:215]
	v_cvt_pk_bf16_f32 v244, v0, v1
	v_cvt_pk_bf16_f32 v245, v2, v3
	v_cvt_pk_bf16_f32 v246, v4, v5
	v_cvt_pk_bf16_f32 v247, v6, v7
	global_store_dwordx2 v234, v[244:245], s[100:101]
	global_store_dwordx2 v235, v[246:247], s[100:101]
	s_add_u32 s100, s100, 0x40000
	s_addc_u32 s101, s101, 0
	v_add_f32_dpp v144, v144, v144 row_shr:1 row_mask:0xf bank_mask:0xf
	v_add_f32_dpp v145, v145, v145 row_shr:1 row_mask:0xf bank_mask:0xf
	s_nop 0
	v_add_f32_dpp v144, v144, v144 row_shr:2 row_mask:0xf bank_mask:0xf
	v_add_f32_dpp v145, v145, v145 row_shr:2 row_mask:0xf bank_mask:0xf
	s_nop 0
	v_add_f32_dpp v144, v144, v144 row_shr:4 row_mask:0xf bank_mask:0xf
	v_add_f32_dpp v145, v145, v145 row_shr:4 row_mask:0xf bank_mask:0xf
	s_nop 0
	v_add_f32_dpp v144, v144, v144 row_shr:8 row_mask:0xf bank_mask:0xf
	v_add_f32_dpp v145, v145, v145 row_shr:8 row_mask:0xf bank_mask:0xf
	s_nop 0
	v_add_f32_dpp v144, v144, v144 row_bcast:15 row_mask:0xa bank_mask:0xf
	v_add_f32_dpp v145, v145, v145 row_bcast:15 row_mask:0xa bank_mask:0xf
	s_nop 0
	v_add_f32_dpp v144, v144, v144 row_bcast:31 row_mask:0xc bank_mask:0xf
	v_add_f32_dpp v145, v145, v145 row_bcast:31 row_mask:0xc bank_mask:0xf
	s_nop 0
	v_readlane_b32 s98, v144, 63
	v_readlane_b32 s99, v145, 63
	s_nop 1
	v_pk_add_f32 v[146:147], s[98:99], v[144:145] neg_lo:[0,1] neg_hi:[0,1]
	v_mul_f32_e64 v152, s98, v228
	v_mul_f32_e64 v153, s99, v228
	v_pk_mul_f32 v[146:147], v[146:147], v[228:229]
	v_exp_f32_e32 v152, v152
	v_exp_f32_e32 v153, v153
	v_exp_f32_e32 v146, v146
	v_exp_f32_e32 v147, v147
	s_nop 0
	v_pk_mul_f32 v[146:147], v[146:147], v[148:149]
	s_nop 0
	v_cvt_pk_bf16_f32 v150, v146, v147
	s_nop 0
	ds_write_b16 v172, v150 offset:0
	ds_write_b16_d16_hi v172, v150 offset:128
	s_and_saveexec_b64 s[20:21], vcc
	ds_write_b64 v163, v[152:153] offset:4096
	s_mov_b64 exec, s[20:21]
	s_waitcnt vmcnt(22)
	ds_write_b64 v28, v[56:57] offset:5120
	ds_write_b32 v30, v58 offset:2080
	s_waitcnt lgkmcnt(0)
	s_barrier
; #define MFMA16(a, b, c) __builtin_amdgcn_mfma_f32_16x16x32_bf16((a), (b), (c), 0, 0, 0)
;     ...
;         for (int n = 0; n < 64; ++n) {
;             const int buf = n & 1;
;             f32x4 a4[4]; bf16x8 vfr[2][2];
; #pragma unroll
;             for (int q = 0; q < 4; ++q) a4[q] = a4n[q];
;             const unsigned kraw = krawn;
; #pragma unroll
;             for (int e = 0; e < 2; ++e)
; #pragma unroll
;                 for (int ks = 0; ks < 2; ++ks) vfr[e][ks] = vfrn[e][ks];
;             if (n + 1 < 64) ldchunk(n + 1);
;             float cum[2];
; #pragma unroll
;             for (int e = 0; e < 2; ++e) {
;                 float z = bb[e];
; #pragma unroll
;                 for (int q = 0; q < 4; ++q) { z += a4[q].x * wa[e][4 * q] + a4[q].y * wa[e][4 * q + 1] + a4[q].z * wa[e][4 * q + 2] + a4[q].w * wa[e][4 * q + 3]; }
;                 cum[e] = (fminf(z, 0.f) - __logf(1.f + __expf(-fabsf(z)))) * (1.f / 16.f);
;             }
; #pragma unroll
;             for (int o = 1; o < 64; o <<= 1) {
;                 const float t0 = __shfl_up(cum[0], o), t1 = __shfl_up(cum[1], o);
;                 if (l >= o) { cum[0] += t0; cum[1] += t1; }
;             }
;             const float tot0 = __shfl(cum[0], 63), tot1 = __shfl(cum[1], 63);
;             kdl[(buf * 16 + 2 * w) * 64 + l] = f2bf(bf2f(kraw & 0xffffu) * __expf(tot0 - cum[0]));
;             kdl[(buf * 16 + 2 * w + 1) * 64 + l] = f2bf(bf2f(kraw >> 16) * __expf(tot1 - cum[1]));
;             if (l == 0) { decl[buf * 16 + 2 * w] = __expf(tot0); decl[buf * 16 + 2 * w + 1] = __expf(tot1); }
;             __syncthreads();
;             const f32x4 d4 = *(const f32x4*)(decl + buf * 16 + (l >> 4) * 4);
; #pragma unroll
;             for (int e = 0; e < 2; ++e) acc[e] = acc[e] * d4;
; #pragma unroll
;             for (int ks = 0; ks < 2; ++ks) {
;                 const bf16x8 af = *(const bf16x8*)(kdl + (buf * 16 + (l & 15)) * 64 + ks * 32 + (l >> 4) * 8);
; #pragma unroll
;                 for (int e = 0; e < 2; ++e) acc[e] = MFMA16(af, vfr[e][ks], acc[e]);
;             }
;             const int cidx = b * 64 + n;
; #pragma unroll
;             for (int e = 0; e < 2; ++e) {
;                 const int vv = (2 * w + e) * 16 + (l & 15);
;                 *(u32x2*)(ST + (((size_t)(cidx * 4 + hh)) * 256 + vv) * 128 + ksl * 16 + (l >> 4) * 4) = pk4(acc[e].x, acc[e].y, acc[e].z, acc[e].w);
;             }
	ds_read_b128 v[8:11], v29 offset:5120
	ds_read_b128 v[12:15], v29 offset:5136
	ds_read_b128 v[16:19], v29 offset:5152
	ds_read_b128 v[20:23], v29 offset:5168
	ds_read_b32 v24, v31 offset:2080
	global_load_dwordx2 v[56:57], v230, s[26:27]
	global_load_dword v58, v231, s[58:59]
	s_add_u32 s26, s26, 0x1000
	s_addc_u32 s27, s27, 0
	s_add_u32 s58, s58, 0x10000
	s_addc_u32 s59, s59, 0
	global_load_dwordx4 v[32:35], v232, s[34:35]
	global_load_dwordx4 v[36:39], v232, s[34:35] offset:64
	global_load_dwordx4 v[40:43], v233, s[34:35]
	global_load_dwordx4 v[44:47], v233, s[34:35] offset:64
	s_add_u32 s34, s34, 0x80
	s_addc_u32 s35, s35, 0
	ds_read_b128 v[154:157], v75 offset:0
	ds_read_b128 v[240:243], v164 offset:4096
	ds_read_b128 v[236:239], v75 offset:64
	s_waitcnt lgkmcnt(3)
	v_pk_fma_f32 v[64:65], v[8:9], v[86:87], v[118:119] op_sel:[0,0,0] op_sel_hi:[0,1,1]
	v_pk_mul_f32 v[66:67], v[16:17], v[102:103] op_sel:[0,0] op_sel_hi:[0,1]
	v_pk_fma_f32 v[64:65], v[8:9], v[88:89], v[64:65] op_sel:[1,0,0] op_sel_hi:[1,1,1]
	v_pk_fma_f32 v[66:67], v[16:17], v[104:105], v[66:67] op_sel:[1,0,0] op_sel_hi:[1,1,1]
	v_pk_fma_f32 v[64:65], v[10:11], v[90:91], v[64:65] op_sel:[0,0,0] op_sel_hi:[0,1,1]
	v_pk_fma_f32 v[66:67], v[18:19], v[106:107], v[66:67] op_sel:[0,0,0] op_sel_hi:[0,1,1]
	v_pk_fma_f32 v[64:65], v[10:11], v[92:93], v[64:65] op_sel:[1,0,0] op_sel_hi:[1,1,1]
	v_pk_fma_f32 v[66:67], v[18:19], v[108:109], v[66:67] op_sel:[1,0,0] op_sel_hi:[1,1,1]
	v_pk_fma_f32 v[64:65], v[12:13], v[94:95], v[64:65] op_sel:[0,0,0] op_sel_hi:[0,1,1]
	v_pk_fma_f32 v[66:67], v[20:21], v[110:111], v[66:67] op_sel:[0,0,0] op_sel_hi:[0,1,1]
	v_pk_fma_f32 v[64:65], v[12:13], v[96:97], v[64:65] op_sel:[1,0,0] op_sel_hi:[1,1,1]
	v_pk_fma_f32 v[66:67], v[20:21], v[112:113], v[66:67] op_sel:[1,0,0] op_sel_hi:[1,1,1]
	v_pk_fma_f32 v[64:65], v[14:15], v[98:99], v[64:65] op_sel:[0,0,0] op_sel_hi:[0,1,1]
	v_pk_fma_f32 v[66:67], v[22:23], v[114:115], v[66:67] op_sel:[0,0,0] op_sel_hi:[0,1,1]
	v_pk_fma_f32 v[64:65], v[14:15], v[100:101], v[64:65] op_sel:[1,0,0] op_sel_hi:[1,1,1]
	v_pk_fma_f32 v[66:67], v[22:23], v[116:117], v[66:67] op_sel:[1,0,0] op_sel_hi:[1,1,1]
	v_lshlrev_b32_e32 v148, 16, v24
	v_pk_add_f32 v[64:65], v[64:65], v[66:67]
	v_and_b32_e32 v149, 0xffff0000, v24
	s_waitcnt lgkmcnt(0)
	v_pk_mul_f32 v[0:1], v[0:1], v[240:241]
	v_pk_mul_f32 v[2:3], v[2:3], v[242:243]
	v_pk_mul_f32 v[4:5], v[4:5], v[240:241]
	v_pk_mul_f32 v[6:7], v[6:7], v[242:243]
	s_waitcnt vmcnt(16)
	s_nop 0
	v_mfma_f32_16x16x32_bf16 v[0:3], v[154:157], v[178:181], v[0:3]
	v_mfma_f32_16x16x32_bf16 v[4:7], v[154:157], v[186:189], v[4:7]
	v_mfma_f32_16x16x32_bf16 v[0:3], v[236:239], v[182:185], v[0:3]
	v_mfma_f32_16x16x32_bf16 v[4:7], v[236:239], v[190:193], v[4:7]
	v_mul_f32_e64 v68, |v64|, v220
	v_mul_f32_e64 v69, |v65|, v220
	v_exp_f32_e32 v68, v68
	v_exp_f32_e32 v69, v69
	v_min_f32_e32 v70, 0, v64
	v_min_f32_e32 v71, 0, v65
	v_pk_add_f32 v[68:69], v[68:69], v[222:223]
	s_nop 0
	v_log_f32_e32 v138, v68
	v_log_f32_e32 v139, v69
	s_nop 0
	v_pk_mul_f32 v[140:141], v[138:139], v[224:225]
	s_nop 0
	v_pk_fma_f32 v[142:143], v[138:139], v[224:225], v[140:141] neg_lo:[0,0,1] neg_hi:[0,0,1]
	s_nop 0
	v_pk_fma_f32 v[142:143], v[138:139], v[226:227], v[142:143]
	s_nop 0
	v_pk_fma_f32 v[142:143], v[138:139], v[224:225], v[142:143]
	s_nop 0
	v_pk_add_f32 v[144:145], v[70:71], v[142:143] neg_lo:[0,1] neg_hi:[0,1]
	s_nop 0
	v_pk_mul_f32 v[144:145], v[144:145], v[214:215]
	v_cvt_pk_bf16_f32 v244, v0, v1
	v_cvt_pk_bf16_f32 v245, v2, v3
	v_cvt_pk_bf16_f32 v246, v4, v5
	v_cvt_pk_bf16_f32 v247, v6, v7
	global_store_dwordx2 v234, v[244:245], s[100:101]
	global_store_dwordx2 v235, v[246:247], s[100:101]
	s_add_u32 s100, s100, 0x40000
	s_addc_u32 s101, s101, 0
	v_add_f32_dpp v144, v144, v144 row_shr:1 row_mask:0xf bank_mask:0xf
	v_add_f32_dpp v145, v145, v145 row_shr:1 row_mask:0xf bank_mask:0xf
	s_nop 0
	v_add_f32_dpp v144, v144, v144 row_shr:2 row_mask:0xf bank_mask:0xf
	v_add_f32_dpp v145, v145, v145 row_shr:2 row_mask:0xf bank_mask:0xf
	s_nop 0
	v_add_f32_dpp v144, v144, v144 row_shr:4 row_mask:0xf bank_mask:0xf
	v_add_f32_dpp v145, v145, v145 row_shr:4 row_mask:0xf bank_mask:0xf
	s_nop 0
	v_add_f32_dpp v144, v144, v144 row_shr:8 row_mask:0xf bank_mask:0xf
	v_add_f32_dpp v145, v145, v145 row_shr:8 row_mask:0xf bank_mask:0xf
	s_nop 0
	v_add_f32_dpp v144, v144, v144 row_bcast:15 row_mask:0xa bank_mask:0xf
	v_add_f32_dpp v145, v145, v145 row_bcast:15 row_mask:0xa bank_mask:0xf
	s_nop 0
	v_add_f32_dpp v144, v144, v144 row_bcast:31 row_mask:0xc bank_mask:0xf
	v_add_f32_dpp v145, v145, v145 row_bcast:31 row_mask:0xc bank_mask:0xf
	s_nop 0
	v_readlane_b32 s98, v144, 63
	v_readlane_b32 s99, v145, 63
	s_nop 1
	v_pk_add_f32 v[146:147], s[98:99], v[144:145] neg_lo:[0,1] neg_hi:[0,1]
	v_mul_f32_e64 v152, s98, v228
	v_mul_f32_e64 v153, s99, v228
	v_pk_mul_f32 v[146:147], v[146:147], v[228:229]
	v_exp_f32_e32 v152, v152
	v_exp_f32_e32 v153, v153
	v_exp_f32_e32 v146, v146
	v_exp_f32_e32 v147, v147
	s_nop 0
	v_pk_mul_f32 v[146:147], v[146:147], v[148:149]
	s_nop 0
	v_cvt_pk_bf16_f32 v150, v146, v147
	s_nop 0
	ds_write_b16 v172, v150 offset:2048
	ds_write_b16_d16_hi v172, v150 offset:2176
	s_and_saveexec_b64 s[20:21], vcc
	ds_write_b64 v163, v[152:153] offset:4160
	s_mov_b64 exec, s[20:21]
	s_waitcnt vmcnt(22)
	ds_write_b64 v28, v[48:49] offset:0
	ds_write_b32 v30, v50 offset:0
	s_waitcnt lgkmcnt(0)
	s_barrier
	ds_read_b128 v[8:11], v29 offset:0
	ds_read_b128 v[12:15], v29 offset:16
	ds_read_b128 v[16:19], v29 offset:32
	ds_read_b128 v[20:23], v29 offset:48
	ds_read_b32 v24, v31 offset:0
	s_mov_b32 s28, 9
; #define MFMA16(a, b, c) __builtin_amdgcn_mfma_f32_16x16x32_bf16((a), (b), (c), 0, 0, 0)
;     ...
;         for (int n = 0; n < 64; ++n) {
;             const int buf = n & 1;
;             f32x4 a4[4]; bf16x8 vfr[2][2];
; #pragma unroll
;             for (int q = 0; q < 4; ++q) a4[q] = a4n[q];
;             const unsigned kraw = krawn;
; #pragma unroll
;             for (int e = 0; e < 2; ++e)
; #pragma unroll
;                 for (int ks = 0; ks < 2; ++ks) vfr[e][ks] = vfrn[e][ks];
;             if (n + 1 < 64) ldchunk(n + 1);
;             float cum[2];
; #pragma unroll
;             for (int e = 0; e < 2; ++e) {
;                 float z = bb[e];
; #pragma unroll
;                 for (int q = 0; q < 4; ++q) { z += a4[q].x * wa[e][4 * q] + a4[q].y * wa[e][4 * q + 1] + a4[q].z * wa[e][4 * q + 2] + a4[q].w * wa[e][4 * q + 3]; }
;                 cum[e] = (fminf(z, 0.f) - __logf(1.f + __expf(-fabsf(z)))) * (1.f / 16.f);
;             }
; #pragma unroll
;             for (int o = 1; o < 64; o <<= 1) {
;                 const float t0 = __shfl_up(cum[0], o), t1 = __shfl_up(cum[1], o);
;                 if (l >= o) { cum[0] += t0; cum[1] += t1; }
;             }
;             const float tot0 = __shfl(cum[0], 63), tot1 = __shfl(cum[1], 63);
;             kdl[(buf * 16 + 2 * w) * 64 + l] = f2bf(bf2f(kraw & 0xffffu) * __expf(tot0 - cum[0]));
;             kdl[(buf * 16 + 2 * w + 1) * 64 + l] = f2bf(bf2f(kraw >> 16) * __expf(tot1 - cum[1]));
;             if (l == 0) { decl[buf * 16 + 2 * w] = __expf(tot0); decl[buf * 16 + 2 * w + 1] = __expf(tot1); }
;             __syncthreads();
;             const f32x4 d4 = *(const f32x4*)(decl + buf * 16 + (l >> 4) * 4);
; #pragma unroll
;             for (int e = 0; e < 2; ++e) acc[e] = acc[e] * d4;
; #pragma unroll
;             for (int ks = 0; ks < 2; ++ks) {
;                 const bf16x8 af = *(const bf16x8*)(kdl + (buf * 16 + (l & 15)) * 64 + ks * 32 + (l >> 4) * 8);
; #pragma unroll
;                 for (int e = 0; e < 2; ++e) acc[e] = MFMA16(af, vfr[e][ks], acc[e]);
;             }
;             const int cidx = b * 64 + n;
; #pragma unroll
;             for (int e = 0; e < 2; ++e) {
;                 const int vv = (2 * w + e) * 16 + (l & 15);
;                 *(u32x2*)(ST + (((size_t)(cidx * 4 + hh)) * 256 + vv) * 128 + ksl * 16 + (l >> 4) * 4) = pk4(acc[e].x, acc[e].y, acc[e].z, acc[e].w);
;             }
.Lgscan_loop:
	global_load_dwordx2 v[48:49], v230, s[26:27]
	global_load_dword v50, v231, s[58:59]
	s_add_u32 s26, s26, 0x1000
	s_addc_u32 s27, s27, 0
	s_add_u32 s58, s58, 0x10000
	s_addc_u32 s59, s59, 0
	global_load_dwordx4 v[178:181], v232, s[34:35]
	global_load_dwordx4 v[182:185], v232, s[34:35] offset:64
	global_load_dwordx4 v[186:189], v233, s[34:35]
	global_load_dwordx4 v[190:193], v233, s[34:35] offset:64
	s_add_u32 s34, s34, 0x80
	s_addc_u32 s35, s35, 0
	ds_read_b128 v[154:157], v75 offset:2048
	ds_read_b128 v[240:243], v164 offset:4160
	ds_read_b128 v[236:239], v75 offset:2112
	s_waitcnt lgkmcnt(3)
	v_pk_fma_f32 v[64:65], v[8:9], v[86:87], v[118:119] op_sel:[0,0,0] op_sel_hi:[0,1,1]
	v_pk_mul_f32 v[66:67], v[16:17], v[102:103] op_sel:[0,0] op_sel_hi:[0,1]
	v_pk_fma_f32 v[64:65], v[8:9], v[88:89], v[64:65] op_sel:[1,0,0] op_sel_hi:[1,1,1]
	v_pk_fma_f32 v[66:67], v[16:17], v[104:105], v[66:67] op_sel:[1,0,0] op_sel_hi:[1,1,1]
	v_pk_fma_f32 v[64:65], v[10:11], v[90:91], v[64:65] op_sel:[0,0,0] op_sel_hi:[0,1,1]
	v_pk_fma_f32 v[66:67], v[18:19], v[106:107], v[66:67] op_sel:[0,0,0] op_sel_hi:[0,1,1]
	v_pk_fma_f32 v[64:65], v[10:11], v[92:93], v[64:65] op_sel:[1,0,0] op_sel_hi:[1,1,1]
	v_pk_fma_f32 v[66:67], v[18:19], v[108:109], v[66:67] op_sel:[1,0,0] op_sel_hi:[1,1,1]
	v_pk_fma_f32 v[64:65], v[12:13], v[94:95], v[64:65] op_sel:[0,0,0] op_sel_hi:[0,1,1]
	v_pk_fma_f32 v[66:67], v[20:21], v[110:111], v[66:67] op_sel:[0,0,0] op_sel_hi:[0,1,1]
	v_pk_fma_f32 v[64:65], v[12:13], v[96:97], v[64:65] op_sel:[1,0,0] op_sel_hi:[1,1,1]
	v_pk_fma_f32 v[66:67], v[20:21], v[112:113], v[66:67] op_sel:[1,0,0] op_sel_hi:[1,1,1]
	v_pk_fma_f32 v[64:65], v[14:15], v[98:99], v[64:65] op_sel:[0,0,0] op_sel_hi:[0,1,1]
	v_pk_fma_f32 v[66:67], v[22:23], v[114:115], v[66:67] op_sel:[0,0,0] op_sel_hi:[0,1,1]
	v_pk_fma_f32 v[64:65], v[14:15], v[100:101], v[64:65] op_sel:[1,0,0] op_sel_hi:[1,1,1]
	v_pk_fma_f32 v[66:67], v[22:23], v[116:117], v[66:67] op_sel:[1,0,0] op_sel_hi:[1,1,1]
	v_lshlrev_b32_e32 v148, 16, v24
	v_pk_add_f32 v[64:65], v[64:65], v[66:67]
	v_and_b32_e32 v149, 0xffff0000, v24
	s_waitcnt lgkmcnt(0)
	v_pk_mul_f32 v[0:1], v[0:1], v[240:241]
	v_pk_mul_f32 v[2:3], v[2:3], v[242:243]
	v_pk_mul_f32 v[4:5], v[4:5], v[240:241]
	v_pk_mul_f32 v[6:7], v[6:7], v[242:243]
	s_waitcnt vmcnt(16)
	s_nop 0
	v_mfma_f32_16x16x32_bf16 v[0:3], v[154:157], v[194:197], v[0:3]
	v_mfma_f32_16x16x32_bf16 v[4:7], v[154:157], v[202:205], v[4:7]
	v_mfma_f32_16x16x32_bf16 v[0:3], v[236:239], v[198:201], v[0:3]
	v_mfma_f32_16x16x32_bf16 v[4:7], v[236:239], v[206:209], v[4:7]
	v_mul_f32_e64 v68, |v64|, v220
	v_mul_f32_e64 v69, |v65|, v220
	v_exp_f32_e32 v68, v68
	v_exp_f32_e32 v69, v69
	v_min_f32_e32 v70, 0, v64
	v_min_f32_e32 v71, 0, v65
	v_pk_add_f32 v[68:69], v[68:69], v[222:223]
	s_nop 0
	v_log_f32_e32 v138, v68
	v_log_f32_e32 v139, v69
	s_nop 0
	v_pk_mul_f32 v[140:141], v[138:139], v[224:225]
	s_nop 0
	v_pk_fma_f32 v[142:143], v[138:139], v[224:225], v[140:141] neg_lo:[0,0,1] neg_hi:[0,0,1]
	s_nop 0
	v_pk_fma_f32 v[142:143], v[138:139], v[226:227], v[142:143]
	s_nop 0
	v_pk_fma_f32 v[142:143], v[138:139], v[224:225], v[142:143]
	s_nop 0
	v_pk_add_f32 v[144:145], v[70:71], v[142:143] neg_lo:[0,1] neg_hi:[0,1]
	s_nop 0
	v_pk_mul_f32 v[144:145], v[144:145], v[214:215]
	v_cvt_pk_bf16_f32 v244, v0, v1
	v_cvt_pk_bf16_f32 v245, v2, v3
	v_cvt_pk_bf16_f32 v246, v4, v5
	v_cvt_pk_bf16_f32 v247, v6, v7
	global_store_dwordx2 v234, v[244:245], s[100:101]
	global_store_dwordx2 v235, v[246:247], s[100:101]
	s_add_u32 s100, s100, 0x40000
	s_addc_u32 s101, s101, 0
	v_add_f32_dpp v144, v144, v144 row_shr:1 row_mask:0xf bank_mask:0xf
	v_add_f32_dpp v145, v145, v145 row_shr:1 row_mask:0xf bank_mask:0xf
	s_nop 0
	v_add_f32_dpp v144, v144, v144 row_shr:2 row_mask:0xf bank_mask:0xf
	v_add_f32_dpp v145, v145, v145 row_shr:2 row_mask:0xf bank_mask:0xf
	s_nop 0
	v_add_f32_dpp v144, v144, v144 row_shr:4 row_mask:0xf bank_mask:0xf
	v_add_f32_dpp v145, v145, v145 row_shr:4 row_mask:0xf bank_mask:0xf
	s_nop 0
	v_add_f32_dpp v144, v144, v144 row_shr:8 row_mask:0xf bank_mask:0xf
	v_add_f32_dpp v145, v145, v145 row_shr:8 row_mask:0xf bank_mask:0xf
	s_nop 0
	v_add_f32_dpp v144, v144, v144 row_bcast:15 row_mask:0xa bank_mask:0xf
	v_add_f32_dpp v145, v145, v145 row_bcast:15 row_mask:0xa bank_mask:0xf
	s_nop 0
	v_add_f32_dpp v144, v144, v144 row_bcast:31 row_mask:0xc bank_mask:0xf
	v_add_f32_dpp v145, v145, v145 row_bcast:31 row_mask:0xc bank_mask:0xf
	s_nop 0
	v_readlane_b32 s98, v144, 63
	v_readlane_b32 s99, v145, 63
	s_nop 1
	v_pk_add_f32 v[146:147], s[98:99], v[144:145] neg_lo:[0,1] neg_hi:[0,1]
	v_mul_f32_e64 v152, s98, v228
	v_mul_f32_e64 v153, s99, v228
	v_pk_mul_f32 v[146:147], v[146:147], v[228:229]
	v_exp_f32_e32 v152, v152
	v_exp_f32_e32 v153, v153
	v_exp_f32_e32 v146, v146
	v_exp_f32_e32 v147, v147
	s_nop 0
	v_pk_mul_f32 v[146:147], v[146:147], v[148:149]
	s_nop 0
	v_cvt_pk_bf16_f32 v150, v146, v147
	s_nop 0
	ds_write_b16 v172, v150 offset:0
	ds_write_b16_d16_hi v172, v150 offset:128
	s_and_saveexec_b64 s[20:21], vcc
	ds_write_b64 v163, v[152:153] offset:4096
	s_mov_b64 exec, s[20:21]
	s_waitcnt vmcnt(22)
	ds_write_b64 v28, v[52:53] offset:5120
	ds_write_b32 v30, v54 offset:2080
	s_waitcnt lgkmcnt(0)
	s_barrier
; #define MFMA16(a, b, c) __builtin_amdgcn_mfma_f32_16x16x32_bf16((a), (b), (c), 0, 0, 0)
;     ...
;         for (int n = 0; n < 64; ++n) {
;             const int buf = n & 1;
;             f32x4 a4[4]; bf16x8 vfr[2][2];
; #pragma unroll
;             for (int q = 0; q < 4; ++q) a4[q] = a4n[q];
;             const unsigned kraw = krawn;
; #pragma unroll
;             for (int e = 0; e < 2; ++e)
; #pragma unroll
;                 for (int ks = 0; ks < 2; ++ks) vfr[e][ks] = vfrn[e][ks];
;             if (n + 1 < 64) ldchunk(n + 1);
;             float cum[2];
; #pragma unroll
;             for (int e = 0; e < 2; ++e) {
;                 float z = bb[e];
; #pragma unroll
;                 for (int q = 0; q < 4; ++q) { z += a4[q].x * wa[e][4 * q] + a4[q].y * wa[e][4 * q + 1] + a4[q].z * wa[e][4 * q + 2] + a4[q].w * wa[e][4 * q + 3]; }
;                 cum[e] = (fminf(z, 0.f) - __logf(1.f + __expf(-fabsf(z)))) * (1.f / 16.f);
;             }
; #pragma unroll
;             for (int o = 1; o < 64; o <<= 1) {
;                 const float t0 = __shfl_up(cum[0], o), t1 = __shfl_up(cum[1], o);
;                 if (l >= o) { cum[0] += t0; cum[1] += t1; }
;             }
;             const float tot0 = __shfl(cum[0], 63), tot1 = __shfl(cum[1], 63);
;             kdl[(buf * 16 + 2 * w) * 64 + l] = f2bf(bf2f(kraw & 0xffffu) * __expf(tot0 - cum[0]));
;             kdl[(buf * 16 + 2 * w + 1) * 64 + l] = f2bf(bf2f(kraw >> 16) * __expf(tot1 - cum[1]));
;             if (l == 0) { decl[buf * 16 + 2 * w] = __expf(tot0); decl[buf * 16 + 2 * w + 1] = __expf(tot1); }
;             __syncthreads();
;             const f32x4 d4 = *(const f32x4*)(decl + buf * 16 + (l >> 4) * 4);
; #pragma unroll
;             for (int e = 0; e < 2; ++e) acc[e] = acc[e] * d4;
; #pragma unroll
;             for (int ks = 0; ks < 2; ++ks) {
;                 const bf16x8 af = *(const bf16x8*)(kdl + (buf * 16 + (l & 15)) * 64 + ks * 32 + (l >> 4) * 8);
; #pragma unroll
;                 for (int e = 0; e < 2; ++e) acc[e] = MFMA16(af, vfr[e][ks], acc[e]);
;             }
;             const int cidx = b * 64 + n;
; #pragma unroll
;             for (int e = 0; e < 2; ++e) {
;                 const int vv = (2 * w + e) * 16 + (l & 15);
;                 *(u32x2*)(ST + (((size_t)(cidx * 4 + hh)) * 256 + vv) * 128 + ksl * 16 + (l >> 4) * 4) = pk4(acc[e].x, acc[e].y, acc[e].z, acc[e].w);
;             }
	ds_read_b128 v[8:11], v29 offset:5120
	ds_read_b128 v[12:15], v29 offset:5136
	ds_read_b128 v[16:19], v29 offset:5152
	ds_read_b128 v[20:23], v29 offset:5168
	ds_read_b32 v24, v31 offset:2080
	global_load_dwordx2 v[52:53], v230, s[26:27]
	global_load_dword v54, v231, s[58:59]
	s_add_u32 s26, s26, 0x1000
	s_addc_u32 s27, s27, 0
	s_add_u32 s58, s58, 0x10000
	s_addc_u32 s59, s59, 0
	global_load_dwordx4 v[194:197], v232, s[34:35]
	global_load_dwordx4 v[198:201], v232, s[34:35] offset:64
	global_load_dwordx4 v[202:205], v233, s[34:35]
	global_load_dwordx4 v[206:209], v233, s[34:35] offset:64
	s_add_u32 s34, s34, 0x80
	s_addc_u32 s35, s35, 0
	ds_read_b128 v[154:157], v75 offset:0
	ds_read_b128 v[240:243], v164 offset:4096
	ds_read_b128 v[236:239], v75 offset:64
	s_waitcnt lgkmcnt(3)
	v_pk_fma_f32 v[64:65], v[8:9], v[86:87], v[118:119] op_sel:[0,0,0] op_sel_hi:[0,1,1]
	v_pk_mul_f32 v[66:67], v[16:17], v[102:103] op_sel:[0,0] op_sel_hi:[0,1]
	v_pk_fma_f32 v[64:65], v[8:9], v[88:89], v[64:65] op_sel:[1,0,0] op_sel_hi:[1,1,1]
	v_pk_fma_f32 v[66:67], v[16:17], v[104:105], v[66:67] op_sel:[1,0,0] op_sel_hi:[1,1,1]
	v_pk_fma_f32 v[64:65], v[10:11], v[90:91], v[64:65] op_sel:[0,0,0] op_sel_hi:[0,1,1]
	v_pk_fma_f32 v[66:67], v[18:19], v[106:107], v[66:67] op_sel:[0,0,0] op_sel_hi:[0,1,1]
	v_pk_fma_f32 v[64:65], v[10:11], v[92:93], v[64:65] op_sel:[1,0,0] op_sel_hi:[1,1,1]
	v_pk_fma_f32 v[66:67], v[18:19], v[108:109], v[66:67] op_sel:[1,0,0] op_sel_hi:[1,1,1]
	v_pk_fma_f32 v[64:65], v[12:13], v[94:95], v[64:65] op_sel:[0,0,0] op_sel_hi:[0,1,1]
	v_pk_fma_f32 v[66:67], v[20:21], v[110:111], v[66:67] op_sel:[0,0,0] op_sel_hi:[0,1,1]
	v_pk_fma_f32 v[64:65], v[12:13], v[96:97], v[64:65] op_sel:[1,0,0] op_sel_hi:[1,1,1]
	v_pk_fma_f32 v[66:67], v[20:21], v[112:113], v[66:67] op_sel:[1,0,0] op_sel_hi:[1,1,1]
	v_pk_fma_f32 v[64:65], v[14:15], v[98:99], v[64:65] op_sel:[0,0,0] op_sel_hi:[0,1,1]
	v_pk_fma_f32 v[66:67], v[22:23], v[114:115], v[66:67] op_sel:[0,0,0] op_sel_hi:[0,1,1]
	v_pk_fma_f32 v[64:65], v[14:15], v[100:101], v[64:65] op_sel:[1,0,0] op_sel_hi:[1,1,1]
	v_pk_fma_f32 v[66:67], v[22:23], v[116:117], v[66:67] op_sel:[1,0,0] op_sel_hi:[1,1,1]
	v_lshlrev_b32_e32 v148, 16, v24
	v_pk_add_f32 v[64:65], v[64:65], v[66:67]
	v_and_b32_e32 v149, 0xffff0000, v24
	s_waitcnt lgkmcnt(0)
	v_pk_mul_f32 v[0:1], v[0:1], v[240:241]
	v_pk_mul_f32 v[2:3], v[2:3], v[242:243]
	v_pk_mul_f32 v[4:5], v[4:5], v[240:241]
	v_pk_mul_f32 v[6:7], v[6:7], v[242:243]
	s_waitcnt vmcnt(16)
	s_nop 0
	v_mfma_f32_16x16x32_bf16 v[0:3], v[154:157], v[32:35], v[0:3]
	v_mfma_f32_16x16x32_bf16 v[4:7], v[154:157], v[40:43], v[4:7]
	v_mfma_f32_16x16x32_bf16 v[0:3], v[236:239], v[36:39], v[0:3]
	v_mfma_f32_16x16x32_bf16 v[4:7], v[236:239], v[44:47], v[4:7]
	v_mul_f32_e64 v68, |v64|, v220
	v_mul_f32_e64 v69, |v65|, v220
	v_exp_f32_e32 v68, v68
	v_exp_f32_e32 v69, v69
	v_min_f32_e32 v70, 0, v64
	v_min_f32_e32 v71, 0, v65
	v_pk_add_f32 v[68:69], v[68:69], v[222:223]
	s_nop 0
	v_log_f32_e32 v138, v68
	v_log_f32_e32 v139, v69
	s_nop 0
	v_pk_mul_f32 v[140:141], v[138:139], v[224:225]
	s_nop 0
	v_pk_fma_f32 v[142:143], v[138:139], v[224:225], v[140:141] neg_lo:[0,0,1] neg_hi:[0,0,1]
	s_nop 0
	v_pk_fma_f32 v[142:143], v[138:139], v[226:227], v[142:143]
	s_nop 0
	v_pk_fma_f32 v[142:143], v[138:139], v[224:225], v[142:143]
	s_nop 0
	v_pk_add_f32 v[144:145], v[70:71], v[142:143] neg_lo:[0,1] neg_hi:[0,1]
	s_nop 0
	v_pk_mul_f32 v[144:145], v[144:145], v[214:215]
	v_cvt_pk_bf16_f32 v244, v0, v1
	v_cvt_pk_bf16_f32 v245, v2, v3
	v_cvt_pk_bf16_f32 v246, v4, v5
	v_cvt_pk_bf16_f32 v247, v6, v7
	global_store_dwordx2 v234, v[244:245], s[100:101]
	global_store_dwordx2 v235, v[246:247], s[100:101]
	s_add_u32 s100, s100, 0x40000
	s_addc_u32 s101, s101, 0
	v_add_f32_dpp v144, v144, v144 row_shr:1 row_mask:0xf bank_mask:0xf
	v_add_f32_dpp v145, v145, v145 row_shr:1 row_mask:0xf bank_mask:0xf
	s_nop 0
	v_add_f32_dpp v144, v144, v144 row_shr:2 row_mask:0xf bank_mask:0xf
	v_add_f32_dpp v145, v145, v145 row_shr:2 row_mask:0xf bank_mask:0xf
	s_nop 0
	v_add_f32_dpp v144, v144, v144 row_shr:4 row_mask:0xf bank_mask:0xf
	v_add_f32_dpp v145, v145, v145 row_shr:4 row_mask:0xf bank_mask:0xf
	s_nop 0
	v_add_f32_dpp v144, v144, v144 row_shr:8 row_mask:0xf bank_mask:0xf
	v_add_f32_dpp v145, v145, v145 row_shr:8 row_mask:0xf bank_mask:0xf
	s_nop 0
	v_add_f32_dpp v144, v144, v144 row_bcast:15 row_mask:0xa bank_mask:0xf
	v_add_f32_dpp v145, v145, v145 row_bcast:15 row_mask:0xa bank_mask:0xf
	s_nop 0
	v_add_f32_dpp v144, v144, v144 row_bcast:31 row_mask:0xc bank_mask:0xf
	v_add_f32_dpp v145, v145, v145 row_bcast:31 row_mask:0xc bank_mask:0xf
	s_nop 0
	v_readlane_b32 s98, v144, 63
	v_readlane_b32 s99, v145, 63
	s_nop 1
	v_pk_add_f32 v[146:147], s[98:99], v[144:145] neg_lo:[0,1] neg_hi:[0,1]
	v_mul_f32_e64 v152, s98, v228
	v_mul_f32_e64 v153, s99, v228
	v_pk_mul_f32 v[146:147], v[146:147], v[228:229]
	v_exp_f32_e32 v152, v152
	v_exp_f32_e32 v153, v153
	v_exp_f32_e32 v146, v146
	v_exp_f32_e32 v147, v147
	s_nop 0
	v_pk_mul_f32 v[146:147], v[146:147], v[148:149]
	s_nop 0
	v_cvt_pk_bf16_f32 v150, v146, v147
	s_nop 0
	ds_write_b16 v172, v150 offset:2048
	ds_write_b16_d16_hi v172, v150 offset:2176
	s_and_saveexec_b64 s[20:21], vcc
	ds_write_b64 v163, v[152:153] offset:4160
	s_mov_b64 exec, s[20:21]
	s_waitcnt vmcnt(22)
	ds_write_b64 v28, v[56:57] offset:0
	ds_write_b32 v30, v58 offset:0
	s_waitcnt lgkmcnt(0)
	s_barrier
; #define MFMA16(a, b, c) __builtin_amdgcn_mfma_f32_16x16x32_bf16((a), (b), (c), 0, 0, 0)
;     ...
;         for (int n = 0; n < 64; ++n) {
;             const int buf = n & 1;
;             f32x4 a4[4]; bf16x8 vfr[2][2];
; #pragma unroll
;             for (int q = 0; q < 4; ++q) a4[q] = a4n[q];
;             const unsigned kraw = krawn;
; #pragma unroll
;             for (int e = 0; e < 2; ++e)
; #pragma unroll
;                 for (int ks = 0; ks < 2; ++ks) vfr[e][ks] = vfrn[e][ks];
;             if (n + 1 < 64) ldchunk(n + 1);
;             float cum[2];
; #pragma unroll
;             for (int e = 0; e < 2; ++e) {
;                 float z = bb[e];
; #pragma unroll
;                 for (int q = 0; q < 4; ++q) { z += a4[q].x * wa[e][4 * q] + a4[q].y * wa[e][4 * q + 1] + a4[q].z * wa[e][4 * q + 2] + a4[q].w * wa[e][4 * q + 3]; }
;                 cum[e] = (fminf(z, 0.f) - __logf(1.f + __expf(-fabsf(z)))) * (1.f / 16.f);
;             }
; #pragma unroll
;             for (int o = 1; o < 64; o <<= 1) {
;                 const float t0 = __shfl_up(cum[0], o), t1 = __shfl_up(cum[1], o);
;                 if (l >= o) { cum[0] += t0; cum[1] += t1; }
;             }
;             const float tot0 = __shfl(cum[0], 63), tot1 = __shfl(cum[1], 63);
;             kdl[(buf * 16 + 2 * w) * 64 + l] = f2bf(bf2f(kraw & 0xffffu) * __expf(tot0 - cum[0]));
;             kdl[(buf * 16 + 2 * w + 1) * 64 + l] = f2bf(bf2f(kraw >> 16) * __expf(tot1 - cum[1]));
;             if (l == 0) { decl[buf * 16 + 2 * w] = __expf(tot0); decl[buf * 16 + 2 * w + 1] = __expf(tot1); }
;             __syncthreads();
;             const f32x4 d4 = *(const f32x4*)(decl + buf * 16 + (l >> 4) * 4);
; #pragma unroll
;             for (int e = 0; e < 2; ++e) acc[e] = acc[e] * d4;
; #pragma unroll
;             for (int ks = 0; ks < 2; ++ks) {
;                 const bf16x8 af = *(const bf16x8*)(kdl + (buf * 16 + (l & 15)) * 64 + ks * 32 + (l >> 4) * 8);
; #pragma unroll
;                 for (int e = 0; e < 2; ++e) acc[e] = MFMA16(af, vfr[e][ks], acc[e]);
;             }
;             const int cidx = b * 64 + n;
; #pragma unroll
;             for (int e = 0; e < 2; ++e) {
;                 const int vv = (2 * w + e) * 16 + (l & 15);
;                 *(u32x2*)(ST + (((size_t)(cidx * 4 + hh)) * 256 + vv) * 128 + ksl * 16 + (l >> 4) * 4) = pk4(acc[e].x, acc[e].y, acc[e].z, acc[e].w);
;             }
	ds_read_b128 v[8:11], v29 offset:0
	ds_read_b128 v[12:15], v29 offset:16
	ds_read_b128 v[16:19], v29 offset:32
	ds_read_b128 v[20:23], v29 offset:48
	ds_read_b32 v24, v31 offset:0
	global_load_dwordx2 v[56:57], v230, s[26:27]
	global_load_dword v58, v231, s[58:59]
	s_add_u32 s26, s26, 0x1000
	s_addc_u32 s27, s27, 0
	s_add_u32 s58, s58, 0x10000
	s_addc_u32 s59, s59, 0
	global_load_dwordx4 v[32:35], v232, s[34:35]
	global_load_dwordx4 v[36:39], v232, s[34:35] offset:64
	global_load_dwordx4 v[40:43], v233, s[34:35]
	global_load_dwordx4 v[44:47], v233, s[34:35] offset:64
	s_add_u32 s34, s34, 0x80
	s_addc_u32 s35, s35, 0
	ds_read_b128 v[154:157], v75 offset:2048
	ds_read_b128 v[240:243], v164 offset:4160
	ds_read_b128 v[236:239], v75 offset:2112
	s_waitcnt lgkmcnt(3)
	v_pk_fma_f32 v[64:65], v[8:9], v[86:87], v[118:119] op_sel:[0,0,0] op_sel_hi:[0,1,1]
	v_pk_mul_f32 v[66:67], v[16:17], v[102:103] op_sel:[0,0] op_sel_hi:[0,1]
	v_pk_fma_f32 v[64:65], v[8:9], v[88:89], v[64:65] op_sel:[1,0,0] op_sel_hi:[1,1,1]
	v_pk_fma_f32 v[66:67], v[16:17], v[104:105], v[66:67] op_sel:[1,0,0] op_sel_hi:[1,1,1]
	v_pk_fma_f32 v[64:65], v[10:11], v[90:91], v[64:65] op_sel:[0,0,0] op_sel_hi:[0,1,1]
	v_pk_fma_f32 v[66:67], v[18:19], v[106:107], v[66:67] op_sel:[0,0,0] op_sel_hi:[0,1,1]
	v_pk_fma_f32 v[64:65], v[10:11], v[92:93], v[64:65] op_sel:[1,0,0] op_sel_hi:[1,1,1]
	v_pk_fma_f32 v[66:67], v[18:19], v[108:109], v[66:67] op_sel:[1,0,0] op_sel_hi:[1,1,1]
	v_pk_fma_f32 v[64:65], v[12:13], v[94:95], v[64:65] op_sel:[0,0,0] op_sel_hi:[0,1,1]
	v_pk_fma_f32 v[66:67], v[20:21], v[110:111], v[66:67] op_sel:[0,0,0] op_sel_hi:[0,1,1]
	v_pk_fma_f32 v[64:65], v[12:13], v[96:97], v[64:65] op_sel:[1,0,0] op_sel_hi:[1,1,1]
	v_pk_fma_f32 v[66:67], v[20:21], v[112:113], v[66:67] op_sel:[1,0,0] op_sel_hi:[1,1,1]
	v_pk_fma_f32 v[64:65], v[14:15], v[98:99], v[64:65] op_sel:[0,0,0] op_sel_hi:[0,1,1]
	v_pk_fma_f32 v[66:67], v[22:23], v[114:115], v[66:67] op_sel:[0,0,0] op_sel_hi:[0,1,1]
	v_pk_fma_f32 v[64:65], v[14:15], v[100:101], v[64:65] op_sel:[1,0,0] op_sel_hi:[1,1,1]
	v_pk_fma_f32 v[66:67], v[22:23], v[116:117], v[66:67] op_sel:[1,0,0] op_sel_hi:[1,1,1]
	v_lshlrev_b32_e32 v148, 16, v24
	v_pk_add_f32 v[64:65], v[64:65], v[66:67]
	v_and_b32_e32 v149, 0xffff0000, v24
	s_waitcnt lgkmcnt(0)
	v_pk_mul_f32 v[0:1], v[0:1], v[240:241]
	v_pk_mul_f32 v[2:3], v[2:3], v[242:243]
	v_pk_mul_f32 v[4:5], v[4:5], v[240:241]
	v_pk_mul_f32 v[6:7], v[6:7], v[242:243]
	s_waitcnt vmcnt(16)
	s_nop 0
	v_mfma_f32_16x16x32_bf16 v[0:3], v[154:157], v[178:181], v[0:3]
	v_mfma_f32_16x16x32_bf16 v[4:7], v[154:157], v[186:189], v[4:7]
	v_mfma_f32_16x16x32_bf16 v[0:3], v[236:239], v[182:185], v[0:3]
	v_mfma_f32_16x16x32_bf16 v[4:7], v[236:239], v[190:193], v[4:7]
	v_mul_f32_e64 v68, |v64|, v220
	v_mul_f32_e64 v69, |v65|, v220
	v_exp_f32_e32 v68, v68
	v_exp_f32_e32 v69, v69
	v_min_f32_e32 v70, 0, v64
	v_min_f32_e32 v71, 0, v65
	v_pk_add_f32 v[68:69], v[68:69], v[222:223]
	s_nop 0
	v_log_f32_e32 v138, v68
	v_log_f32_e32 v139, v69
	s_nop 0
	v_pk_mul_f32 v[140:141], v[138:139], v[224:225]
	s_nop 0
	v_pk_fma_f32 v[142:143], v[138:139], v[224:225], v[140:141] neg_lo:[0,0,1] neg_hi:[0,0,1]
	s_nop 0
	v_pk_fma_f32 v[142:143], v[138:139], v[226:227], v[142:143]
	s_nop 0
	v_pk_fma_f32 v[142:143], v[138:139], v[224:225], v[142:143]
	s_nop 0
	v_pk_add_f32 v[144:145], v[70:71], v[142:143] neg_lo:[0,1] neg_hi:[0,1]
	s_nop 0
	v_pk_mul_f32 v[144:145], v[144:145], v[214:215]
	v_cvt_pk_bf16_f32 v244, v0, v1
	v_cvt_pk_bf16_f32 v245, v2, v3
	v_cvt_pk_bf16_f32 v246, v4, v5
	v_cvt_pk_bf16_f32 v247, v6, v7
	global_store_dwordx2 v234, v[244:245], s[100:101]
	global_store_dwordx2 v235, v[246:247], s[100:101]
	s_add_u32 s100, s100, 0x40000
	s_addc_u32 s101, s101, 0
	v_add_f32_dpp v144, v144, v144 row_shr:1 row_mask:0xf bank_mask:0xf
	v_add_f32_dpp v145, v145, v145 row_shr:1 row_mask:0xf bank_mask:0xf
	s_nop 0
	v_add_f32_dpp v144, v144, v144 row_shr:2 row_mask:0xf bank_mask:0xf
	v_add_f32_dpp v145, v145, v145 row_shr:2 row_mask:0xf bank_mask:0xf
	s_nop 0
	v_add_f32_dpp v144, v144, v144 row_shr:4 row_mask:0xf bank_mask:0xf
	v_add_f32_dpp v145, v145, v145 row_shr:4 row_mask:0xf bank_mask:0xf
	s_nop 0
	v_add_f32_dpp v144, v144, v144 row_shr:8 row_mask:0xf bank_mask:0xf
	v_add_f32_dpp v145, v145, v145 row_shr:8 row_mask:0xf bank_mask:0xf
	s_nop 0
	v_add_f32_dpp v144, v144, v144 row_bcast:15 row_mask:0xa bank_mask:0xf
	v_add_f32_dpp v145, v145, v145 row_bcast:15 row_mask:0xa bank_mask:0xf
	s_nop 0
	v_add_f32_dpp v144, v144, v144 row_bcast:31 row_mask:0xc bank_mask:0xf
	v_add_f32_dpp v145, v145, v145 row_bcast:31 row_mask:0xc bank_mask:0xf
	s_nop 0
	v_readlane_b32 s98, v144, 63
	v_readlane_b32 s99, v145, 63
	s_nop 1
	v_pk_add_f32 v[146:147], s[98:99], v[144:145] neg_lo:[0,1] neg_hi:[0,1]
	v_mul_f32_e64 v152, s98, v228
	v_mul_f32_e64 v153, s99, v228
	v_pk_mul_f32 v[146:147], v[146:147], v[228:229]
	v_exp_f32_e32 v152, v152
	v_exp_f32_e32 v153, v153
	v_exp_f32_e32 v146, v146
	v_exp_f32_e32 v147, v147
	s_nop 0
	v_pk_mul_f32 v[146:147], v[146:147], v[148:149]
	s_nop 0
	v_cvt_pk_bf16_f32 v150, v146, v147
	s_nop 0
	ds_write_b16 v172, v150 offset:0
	ds_write_b16_d16_hi v172, v150 offset:128
	s_and_saveexec_b64 s[20:21], vcc
	ds_write_b64 v163, v[152:153] offset:4096
	s_mov_b64 exec, s[20:21]
	s_waitcnt vmcnt(22)
	ds_write_b64 v28, v[48:49] offset:5120
	ds_write_b32 v30, v50 offset:2080
	s_waitcnt lgkmcnt(0)
	s_barrier
; #define MFMA16(a, b, c) __builtin_amdgcn_mfma_f32_16x16x32_bf16((a), (b), (c), 0, 0, 0)
;     ...
;         for (int n = 0; n < 64; ++n) {
;             const int buf = n & 1;
;             f32x4 a4[4]; bf16x8 vfr[2][2];
; #pragma unroll
;             for (int q = 0; q < 4; ++q) a4[q] = a4n[q];
;             const unsigned kraw = krawn;
; #pragma unroll
;             for (int e = 0; e < 2; ++e)
; #pragma unroll
;                 for (int ks = 0; ks < 2; ++ks) vfr[e][ks] = vfrn[e][ks];
;             if (n + 1 < 64) ldchunk(n + 1);
;             float cum[2];
; #pragma unroll
;             for (int e = 0; e < 2; ++e) {
;                 float z = bb[e];
; #pragma unroll
;                 for (int q = 0; q < 4; ++q) { z += a4[q].x * wa[e][4 * q] + a4[q].y * wa[e][4 * q + 1] + a4[q].z * wa[e][4 * q + 2] + a4[q].w * wa[e][4 * q + 3]; }
;                 cum[e] = (fminf(z, 0.f) - __logf(1.f + __expf(-fabsf(z)))) * (1.f / 16.f);
;             }
; #pragma unroll
;             for (int o = 1; o < 64; o <<= 1) {
;                 const float t0 = __shfl_up(cum[0], o), t1 = __shfl_up(cum[1], o);
;                 if (l >= o) { cum[0] += t0; cum[1] += t1; }
;             }
;             const float tot0 = __shfl(cum[0], 63), tot1 = __shfl(cum[1], 63);
;             kdl[(buf * 16 + 2 * w) * 64 + l] = f2bf(bf2f(kraw & 0xffffu) * __expf(tot0 - cum[0]));
;             kdl[(buf * 16 + 2 * w + 1) * 64 + l] = f2bf(bf2f(kraw >> 16) * __expf(tot1 - cum[1]));
;             if (l == 0) { decl[buf * 16 + 2 * w] = __expf(tot0); decl[buf * 16 + 2 * w + 1] = __expf(tot1); }
;             __syncthreads();
;             const f32x4 d4 = *(const f32x4*)(decl + buf * 16 + (l >> 4) * 4);
; #pragma unroll
;             for (int e = 0; e < 2; ++e) acc[e] = acc[e] * d4;
; #pragma unroll
;             for (int ks = 0; ks < 2; ++ks) {
;                 const bf16x8 af = *(const bf16x8*)(kdl + (buf * 16 + (l & 15)) * 64 + ks * 32 + (l >> 4) * 8);
; #pragma unroll
;                 for (int e = 0; e < 2; ++e) acc[e] = MFMA16(af, vfr[e][ks], acc[e]);
;             }
;             const int cidx = b * 64 + n;
; #pragma unroll
;             for (int e = 0; e < 2; ++e) {
;                 const int vv = (2 * w + e) * 16 + (l & 15);
;                 *(u32x2*)(ST + (((size_t)(cidx * 4 + hh)) * 256 + vv) * 128 + ksl * 16 + (l >> 4) * 4) = pk4(acc[e].x, acc[e].y, acc[e].z, acc[e].w);
;             }
	ds_read_b128 v[8:11], v29 offset:5120
	ds_read_b128 v[12:15], v29 offset:5136
	ds_read_b128 v[16:19], v29 offset:5152
	ds_read_b128 v[20:23], v29 offset:5168
	ds_read_b32 v24, v31 offset:2080
	global_load_dwordx2 v[48:49], v230, s[26:27]
	global_load_dword v50, v231, s[58:59]
	s_add_u32 s26, s26, 0x1000
	s_addc_u32 s27, s27, 0
	s_add_u32 s58, s58, 0x10000
	s_addc_u32 s59, s59, 0
	global_load_dwordx4 v[178:181], v232, s[34:35]
	global_load_dwordx4 v[182:185], v232, s[34:35] offset:64
	global_load_dwordx4 v[186:189], v233, s[34:35]
	global_load_dwordx4 v[190:193], v233, s[34:35] offset:64
	s_add_u32 s34, s34, 0x80
	s_addc_u32 s35, s35, 0
	ds_read_b128 v[154:157], v75 offset:0
	ds_read_b128 v[240:243], v164 offset:4096
	ds_read_b128 v[236:239], v75 offset:64
	s_waitcnt lgkmcnt(3)
	v_pk_fma_f32 v[64:65], v[8:9], v[86:87], v[118:119] op_sel:[0,0,0] op_sel_hi:[0,1,1]
	v_pk_mul_f32 v[66:67], v[16:17], v[102:103] op_sel:[0,0] op_sel_hi:[0,1]
	v_pk_fma_f32 v[64:65], v[8:9], v[88:89], v[64:65] op_sel:[1,0,0] op_sel_hi:[1,1,1]
	v_pk_fma_f32 v[66:67], v[16:17], v[104:105], v[66:67] op_sel:[1,0,0] op_sel_hi:[1,1,1]
	v_pk_fma_f32 v[64:65], v[10:11], v[90:91], v[64:65] op_sel:[0,0,0] op_sel_hi:[0,1,1]
	v_pk_fma_f32 v[66:67], v[18:19], v[106:107], v[66:67] op_sel:[0,0,0] op_sel_hi:[0,1,1]
	v_pk_fma_f32 v[64:65], v[10:11], v[92:93], v[64:65] op_sel:[1,0,0] op_sel_hi:[1,1,1]
	v_pk_fma_f32 v[66:67], v[18:19], v[108:109], v[66:67] op_sel:[1,0,0] op_sel_hi:[1,1,1]
	v_pk_fma_f32 v[64:65], v[12:13], v[94:95], v[64:65] op_sel:[0,0,0] op_sel_hi:[0,1,1]
	v_pk_fma_f32 v[66:67], v[20:21], v[110:111], v[66:67] op_sel:[0,0,0] op_sel_hi:[0,1,1]
	v_pk_fma_f32 v[64:65], v[12:13], v[96:97], v[64:65] op_sel:[1,0,0] op_sel_hi:[1,1,1]
	v_pk_fma_f32 v[66:67], v[20:21], v[112:113], v[66:67] op_sel:[1,0,0] op_sel_hi:[1,1,1]
	v_pk_fma_f32 v[64:65], v[14:15], v[98:99], v[64:65] op_sel:[0,0,0] op_sel_hi:[0,1,1]
	v_pk_fma_f32 v[66:67], v[22:23], v[114:115], v[66:67] op_sel:[0,0,0] op_sel_hi:[0,1,1]
	v_pk_fma_f32 v[64:65], v[14:15], v[100:101], v[64:65] op_sel:[1,0,0] op_sel_hi:[1,1,1]
	v_pk_fma_f32 v[66:67], v[22:23], v[116:117], v[66:67] op_sel:[1,0,0] op_sel_hi:[1,1,1]
	v_lshlrev_b32_e32 v148, 16, v24
	v_pk_add_f32 v[64:65], v[64:65], v[66:67]
	v_and_b32_e32 v149, 0xffff0000, v24
	s_waitcnt lgkmcnt(0)
	v_pk_mul_f32 v[0:1], v[0:1], v[240:241]
	v_pk_mul_f32 v[2:3], v[2:3], v[242:243]
	v_pk_mul_f32 v[4:5], v[4:5], v[240:241]
	v_pk_mul_f32 v[6:7], v[6:7], v[242:243]
	s_waitcnt vmcnt(16)
	s_nop 0
	v_mfma_f32_16x16x32_bf16 v[0:3], v[154:157], v[194:197], v[0:3]
	v_mfma_f32_16x16x32_bf16 v[4:7], v[154:157], v[202:205], v[4:7]
	v_mfma_f32_16x16x32_bf16 v[0:3], v[236:239], v[198:201], v[0:3]
	v_mfma_f32_16x16x32_bf16 v[4:7], v[236:239], v[206:209], v[4:7]
	v_mul_f32_e64 v68, |v64|, v220
	v_mul_f32_e64 v69, |v65|, v220
	v_exp_f32_e32 v68, v68
	v_exp_f32_e32 v69, v69
	v_min_f32_e32 v70, 0, v64
	v_min_f32_e32 v71, 0, v65
	v_pk_add_f32 v[68:69], v[68:69], v[222:223]
	s_nop 0
	v_log_f32_e32 v138, v68
	v_log_f32_e32 v139, v69
	s_nop 0
	v_pk_mul_f32 v[140:141], v[138:139], v[224:225]
	s_nop 0
	v_pk_fma_f32 v[142:143], v[138:139], v[224:225], v[140:141] neg_lo:[0,0,1] neg_hi:[0,0,1]
	s_nop 0
	v_pk_fma_f32 v[142:143], v[138:139], v[226:227], v[142:143]
	s_nop 0
	v_pk_fma_f32 v[142:143], v[138:139], v[224:225], v[142:143]
	s_nop 0
	v_pk_add_f32 v[144:145], v[70:71], v[142:143] neg_lo:[0,1] neg_hi:[0,1]
	s_nop 0
	v_pk_mul_f32 v[144:145], v[144:145], v[214:215]
	v_cvt_pk_bf16_f32 v244, v0, v1
	v_cvt_pk_bf16_f32 v245, v2, v3
	v_cvt_pk_bf16_f32 v246, v4, v5
	v_cvt_pk_bf16_f32 v247, v6, v7
	global_store_dwordx2 v234, v[244:245], s[100:101]
	global_store_dwordx2 v235, v[246:247], s[100:101]
	s_add_u32 s100, s100, 0x40000
	s_addc_u32 s101, s101, 0
	v_add_f32_dpp v144, v144, v144 row_shr:1 row_mask:0xf bank_mask:0xf
	v_add_f32_dpp v145, v145, v145 row_shr:1 row_mask:0xf bank_mask:0xf
	s_nop 0
	v_add_f32_dpp v144, v144, v144 row_shr:2 row_mask:0xf bank_mask:0xf
	v_add_f32_dpp v145, v145, v145 row_shr:2 row_mask:0xf bank_mask:0xf
	s_nop 0
	v_add_f32_dpp v144, v144, v144 row_shr:4 row_mask:0xf bank_mask:0xf
	v_add_f32_dpp v145, v145, v145 row_shr:4 row_mask:0xf bank_mask:0xf
	s_nop 0
	v_add_f32_dpp v144, v144, v144 row_shr:8 row_mask:0xf bank_mask:0xf
	v_add_f32_dpp v145, v145, v145 row_shr:8 row_mask:0xf bank_mask:0xf
	s_nop 0
	v_add_f32_dpp v144, v144, v144 row_bcast:15 row_mask:0xa bank_mask:0xf
	v_add_f32_dpp v145, v145, v145 row_bcast:15 row_mask:0xa bank_mask:0xf
	s_nop 0
	v_add_f32_dpp v144, v144, v144 row_bcast:31 row_mask:0xc bank_mask:0xf
	v_add_f32_dpp v145, v145, v145 row_bcast:31 row_mask:0xc bank_mask:0xf
	s_nop 0
	v_readlane_b32 s98, v144, 63
	v_readlane_b32 s99, v145, 63
	s_nop 1
	v_pk_add_f32 v[146:147], s[98:99], v[144:145] neg_lo:[0,1] neg_hi:[0,1]
	v_mul_f32_e64 v152, s98, v228
	v_mul_f32_e64 v153, s99, v228
	v_pk_mul_f32 v[146:147], v[146:147], v[228:229]
	v_exp_f32_e32 v152, v152
	v_exp_f32_e32 v153, v153
	v_exp_f32_e32 v146, v146
	v_exp_f32_e32 v147, v147
	s_nop 0
	v_pk_mul_f32 v[146:147], v[146:147], v[148:149]
	s_nop 0
	v_cvt_pk_bf16_f32 v150, v146, v147
	s_nop 0
	ds_write_b16 v172, v150 offset:2048
	ds_write_b16_d16_hi v172, v150 offset:2176
	s_and_saveexec_b64 s[20:21], vcc
	ds_write_b64 v163, v[152:153] offset:4160
	s_mov_b64 exec, s[20:21]
	s_waitcnt vmcnt(22)
	ds_write_b64 v28, v[52:53] offset:0
	ds_write_b32 v30, v54 offset:0
	s_waitcnt lgkmcnt(0)
	s_barrier
; #define MFMA16(a, b, c) __builtin_amdgcn_mfma_f32_16x16x32_bf16((a), (b), (c), 0, 0, 0)
;     ...
;         for (int n = 0; n < 64; ++n) {
;             const int buf = n & 1;
;             f32x4 a4[4]; bf16x8 vfr[2][2];
; #pragma unroll
;             for (int q = 0; q < 4; ++q) a4[q] = a4n[q];
;             const unsigned kraw = krawn;
; #pragma unroll
;             for (int e = 0; e < 2; ++e)
; #pragma unroll
;                 for (int ks = 0; ks < 2; ++ks) vfr[e][ks] = vfrn[e][ks];
;             if (n + 1 < 64) ldchunk(n + 1);
;             float cum[2];
; #pragma unroll
;             for (int e = 0; e < 2; ++e) {
;                 float z = bb[e];
; #pragma unroll
;                 for (int q = 0; q < 4; ++q) { z += a4[q].x * wa[e][4 * q] + a4[q].y * wa[e][4 * q + 1] + a4[q].z * wa[e][4 * q + 2] + a4[q].w * wa[e][4 * q + 3]; }
;                 cum[e] = (fminf(z, 0.f) - __logf(1.f + __expf(-fabsf(z)))) * (1.f / 16.f);
;             }
; #pragma unroll
;             for (int o = 1; o < 64; o <<= 1) {
;                 const float t0 = __shfl_up(cum[0], o), t1 = __shfl_up(cum[1], o);
;                 if (l >= o) { cum[0] += t0; cum[1] += t1; }
;             }
;             const float tot0 = __shfl(cum[0], 63), tot1 = __shfl(cum[1], 63);
;             kdl[(buf * 16 + 2 * w) * 64 + l] = f2bf(bf2f(kraw & 0xffffu) * __expf(tot0 - cum[0]));
;             kdl[(buf * 16 + 2 * w + 1) * 64 + l] = f2bf(bf2f(kraw >> 16) * __expf(tot1 - cum[1]));
;             if (l == 0) { decl[buf * 16 + 2 * w] = __expf(tot0); decl[buf * 16 + 2 * w + 1] = __expf(tot1); }
;             __syncthreads();
;             const f32x4 d4 = *(const f32x4*)(decl + buf * 16 + (l >> 4) * 4);
; #pragma unroll
;             for (int e = 0; e < 2; ++e) acc[e] = acc[e] * d4;
; #pragma unroll
;             for (int ks = 0; ks < 2; ++ks) {
;                 const bf16x8 af = *(const bf16x8*)(kdl + (buf * 16 + (l & 15)) * 64 + ks * 32 + (l >> 4) * 8);
; #pragma unroll
;                 for (int e = 0; e < 2; ++e) acc[e] = MFMA16(af, vfr[e][ks], acc[e]);
;             }
;             const int cidx = b * 64 + n;
; #pragma unroll
;             for (int e = 0; e < 2; ++e) {
;                 const int vv = (2 * w + e) * 16 + (l & 15);
;                 *(u32x2*)(ST + (((size_t)(cidx * 4 + hh)) * 256 + vv) * 128 + ksl * 16 + (l >> 4) * 4) = pk4(acc[e].x, acc[e].y, acc[e].z, acc[e].w);
;             }
	ds_read_b128 v[8:11], v29 offset:0
	ds_read_b128 v[12:15], v29 offset:16
	ds_read_b128 v[16:19], v29 offset:32
	ds_read_b128 v[20:23], v29 offset:48
	ds_read_b32 v24, v31 offset:0
	global_load_dwordx2 v[52:53], v230, s[26:27]
	global_load_dword v54, v231, s[58:59]
	s_add_u32 s26, s26, 0x1000
	s_addc_u32 s27, s27, 0
	s_add_u32 s58, s58, 0x10000
	s_addc_u32 s59, s59, 0
	global_load_dwordx4 v[194:197], v232, s[34:35]
	global_load_dwordx4 v[198:201], v232, s[34:35] offset:64
	global_load_dwordx4 v[202:205], v233, s[34:35]
	global_load_dwordx4 v[206:209], v233, s[34:35] offset:64
	s_add_u32 s34, s34, 0x80
	s_addc_u32 s35, s35, 0
	ds_read_b128 v[154:157], v75 offset:2048
	ds_read_b128 v[240:243], v164 offset:4160
	ds_read_b128 v[236:239], v75 offset:2112
	s_waitcnt lgkmcnt(3)
	v_pk_fma_f32 v[64:65], v[8:9], v[86:87], v[118:119] op_sel:[0,0,0] op_sel_hi:[0,1,1]
	v_pk_mul_f32 v[66:67], v[16:17], v[102:103] op_sel:[0,0] op_sel_hi:[0,1]
	v_pk_fma_f32 v[64:65], v[8:9], v[88:89], v[64:65] op_sel:[1,0,0] op_sel_hi:[1,1,1]
	v_pk_fma_f32 v[66:67], v[16:17], v[104:105], v[66:67] op_sel:[1,0,0] op_sel_hi:[1,1,1]
	v_pk_fma_f32 v[64:65], v[10:11], v[90:91], v[64:65] op_sel:[0,0,0] op_sel_hi:[0,1,1]
	v_pk_fma_f32 v[66:67], v[18:19], v[106:107], v[66:67] op_sel:[0,0,0] op_sel_hi:[0,1,1]
	v_pk_fma_f32 v[64:65], v[10:11], v[92:93], v[64:65] op_sel:[1,0,0] op_sel_hi:[1,1,1]
	v_pk_fma_f32 v[66:67], v[18:19], v[108:109], v[66:67] op_sel:[1,0,0] op_sel_hi:[1,1,1]
	v_pk_fma_f32 v[64:65], v[12:13], v[94:95], v[64:65] op_sel:[0,0,0] op_sel_hi:[0,1,1]
	v_pk_fma_f32 v[66:67], v[20:21], v[110:111], v[66:67] op_sel:[0,0,0] op_sel_hi:[0,1,1]
	v_pk_fma_f32 v[64:65], v[12:13], v[96:97], v[64:65] op_sel:[1,0,0] op_sel_hi:[1,1,1]
	v_pk_fma_f32 v[66:67], v[20:21], v[112:113], v[66:67] op_sel:[1,0,0] op_sel_hi:[1,1,1]
	v_pk_fma_f32 v[64:65], v[14:15], v[98:99], v[64:65] op_sel:[0,0,0] op_sel_hi:[0,1,1]
	v_pk_fma_f32 v[66:67], v[22:23], v[114:115], v[66:67] op_sel:[0,0,0] op_sel_hi:[0,1,1]
	v_pk_fma_f32 v[64:65], v[14:15], v[100:101], v[64:65] op_sel:[1,0,0] op_sel_hi:[1,1,1]
	v_pk_fma_f32 v[66:67], v[22:23], v[116:117], v[66:67] op_sel:[1,0,0] op_sel_hi:[1,1,1]
	v_lshlrev_b32_e32 v148, 16, v24
	v_pk_add_f32 v[64:65], v[64:65], v[66:67]
	v_and_b32_e32 v149, 0xffff0000, v24
	s_waitcnt lgkmcnt(0)
	v_pk_mul_f32 v[0:1], v[0:1], v[240:241]
	v_pk_mul_f32 v[2:3], v[2:3], v[242:243]
	v_pk_mul_f32 v[4:5], v[4:5], v[240:241]
	v_pk_mul_f32 v[6:7], v[6:7], v[242:243]
	s_waitcnt vmcnt(16)
	s_nop 0
	v_mfma_f32_16x16x32_bf16 v[0:3], v[154:157], v[32:35], v[0:3]
	v_mfma_f32_16x16x32_bf16 v[4:7], v[154:157], v[40:43], v[4:7]
	v_mfma_f32_16x16x32_bf16 v[0:3], v[236:239], v[36:39], v[0:3]
	v_mfma_f32_16x16x32_bf16 v[4:7], v[236:239], v[44:47], v[4:7]
	v_mul_f32_e64 v68, |v64|, v220
	v_mul_f32_e64 v69, |v65|, v220
	v_exp_f32_e32 v68, v68
	v_exp_f32_e32 v69, v69
	v_min_f32_e32 v70, 0, v64
	v_min_f32_e32 v71, 0, v65
	v_pk_add_f32 v[68:69], v[68:69], v[222:223]
	s_nop 0
	v_log_f32_e32 v138, v68
	v_log_f32_e32 v139, v69
	s_nop 0
	v_pk_mul_f32 v[140:141], v[138:139], v[224:225]
	s_nop 0
	v_pk_fma_f32 v[142:143], v[138:139], v[224:225], v[140:141] neg_lo:[0,0,1] neg_hi:[0,0,1]
	s_nop 0
	v_pk_fma_f32 v[142:143], v[138:139], v[226:227], v[142:143]
	s_nop 0
	v_pk_fma_f32 v[142:143], v[138:139], v[224:225], v[142:143]
	s_nop 0
	v_pk_add_f32 v[144:145], v[70:71], v[142:143] neg_lo:[0,1] neg_hi:[0,1]
	s_nop 0
	v_pk_mul_f32 v[144:145], v[144:145], v[214:215]
	v_cvt_pk_bf16_f32 v244, v0, v1
	v_cvt_pk_bf16_f32 v245, v2, v3
	v_cvt_pk_bf16_f32 v246, v4, v5
	v_cvt_pk_bf16_f32 v247, v6, v7
	global_store_dwordx2 v234, v[244:245], s[100:101]
	global_store_dwordx2 v235, v[246:247], s[100:101]
	s_add_u32 s100, s100, 0x40000
	s_addc_u32 s101, s101, 0
	v_add_f32_dpp v144, v144, v144 row_shr:1 row_mask:0xf bank_mask:0xf
	v_add_f32_dpp v145, v145, v145 row_shr:1 row_mask:0xf bank_mask:0xf
	s_nop 0
	v_add_f32_dpp v144, v144, v144 row_shr:2 row_mask:0xf bank_mask:0xf
	v_add_f32_dpp v145, v145, v145 row_shr:2 row_mask:0xf bank_mask:0xf
	s_nop 0
	v_add_f32_dpp v144, v144, v144 row_shr:4 row_mask:0xf bank_mask:0xf
	v_add_f32_dpp v145, v145, v145 row_shr:4 row_mask:0xf bank_mask:0xf
	s_nop 0
	v_add_f32_dpp v144, v144, v144 row_shr:8 row_mask:0xf bank_mask:0xf
	v_add_f32_dpp v145, v145, v145 row_shr:8 row_mask:0xf bank_mask:0xf
	s_nop 0
	v_add_f32_dpp v144, v144, v144 row_bcast:15 row_mask:0xa bank_mask:0xf
	v_add_f32_dpp v145, v145, v145 row_bcast:15 row_mask:0xa bank_mask:0xf
	s_nop 0
	v_add_f32_dpp v144, v144, v144 row_bcast:31 row_mask:0xc bank_mask:0xf
	v_add_f32_dpp v145, v145, v145 row_bcast:31 row_mask:0xc bank_mask:0xf
	s_nop 0
	v_readlane_b32 s98, v144, 63
	v_readlane_b32 s99, v145, 63
	s_nop 1
	v_pk_add_f32 v[146:147], s[98:99], v[144:145] neg_lo:[0,1] neg_hi:[0,1]
	v_mul_f32_e64 v152, s98, v228
	v_mul_f32_e64 v153, s99, v228
	v_pk_mul_f32 v[146:147], v[146:147], v[228:229]
	v_exp_f32_e32 v152, v152
	v_exp_f32_e32 v153, v153
	v_exp_f32_e32 v146, v146
	v_exp_f32_e32 v147, v147
	s_nop 0
	v_pk_mul_f32 v[146:147], v[146:147], v[148:149]
	s_nop 0
	v_cvt_pk_bf16_f32 v150, v146, v147
	s_nop 0
	ds_write_b16 v172, v150 offset:0
	ds_write_b16_d16_hi v172, v150 offset:128
	s_and_saveexec_b64 s[20:21], vcc
	ds_write_b64 v163, v[152:153] offset:4096
	s_mov_b64 exec, s[20:21]
	s_waitcnt vmcnt(22)
	ds_write_b64 v28, v[56:57] offset:5120
	ds_write_b32 v30, v58 offset:2080
	s_waitcnt lgkmcnt(0)
	s_barrier
; #define MFMA16(a, b, c) __builtin_amdgcn_mfma_f32_16x16x32_bf16((a), (b), (c), 0, 0, 0)
;     ...
;         for (int n = 0; n < 64; ++n) {
;             const int buf = n & 1;
;             f32x4 a4[4]; bf16x8 vfr[2][2];
; #pragma unroll
;             for (int q = 0; q < 4; ++q) a4[q] = a4n[q];
;             const unsigned kraw = krawn;
; #pragma unroll
;             for (int e = 0; e < 2; ++e)
; #pragma unroll
;                 for (int ks = 0; ks < 2; ++ks) vfr[e][ks] = vfrn[e][ks];
;             if (n + 1 < 64) ldchunk(n + 1);
;             float cum[2];
; #pragma unroll
;             for (int e = 0; e < 2; ++e) {
;                 float z = bb[e];
; #pragma unroll
;                 for (int q = 0; q < 4; ++q) { z += a4[q].x * wa[e][4 * q] + a4[q].y * wa[e][4 * q + 1] + a4[q].z * wa[e][4 * q + 2] + a4[q].w * wa[e][4 * q + 3]; }
;                 cum[e] = (fminf(z, 0.f) - __logf(1.f + __expf(-fabsf(z)))) * (1.f / 16.f);
;             }
; #pragma unroll
;             for (int o = 1; o < 64; o <<= 1) {
;                 const float t0 = __shfl_up(cum[0], o), t1 = __shfl_up(cum[1], o);
;                 if (l >= o) { cum[0] += t0; cum[1] += t1; }
;             }
;             const float tot0 = __shfl(cum[0], 63), tot1 = __shfl(cum[1], 63);
;             kdl[(buf * 16 + 2 * w) * 64 + l] = f2bf(bf2f(kraw & 0xffffu) * __expf(tot0 - cum[0]));
;             kdl[(buf * 16 + 2 * w + 1) * 64 + l] = f2bf(bf2f(kraw >> 16) * __expf(tot1 - cum[1]));
;             if (l == 0) { decl[buf * 16 + 2 * w] = __expf(tot0); decl[buf * 16 + 2 * w + 1] = __expf(tot1); }
;             __syncthreads();
;             const f32x4 d4 = *(const f32x4*)(decl + buf * 16 + (l >> 4) * 4);
; #pragma unroll
;             for (int e = 0; e < 2; ++e) acc[e] = acc[e] * d4;
; #pragma unroll
;             for (int ks = 0; ks < 2; ++ks) {
;                 const bf16x8 af = *(const bf16x8*)(kdl + (buf * 16 + (l & 15)) * 64 + ks * 32 + (l >> 4) * 8);
; #pragma unroll
;                 for (int e = 0; e < 2; ++e) acc[e] = MFMA16(af, vfr[e][ks], acc[e]);
;             }
;             const int cidx = b * 64 + n;
; #pragma unroll
;             for (int e = 0; e < 2; ++e) {
;                 const int vv = (2 * w + e) * 16 + (l & 15);
;                 *(u32x2*)(ST + (((size_t)(cidx * 4 + hh)) * 256 + vv) * 128 + ksl * 16 + (l >> 4) * 4) = pk4(acc[e].x, acc[e].y, acc[e].z, acc[e].w);
;             }
	ds_read_b128 v[8:11], v29 offset:5120
	ds_read_b128 v[12:15], v29 offset:5136
	ds_read_b128 v[16:19], v29 offset:5152
	ds_read_b128 v[20:23], v29 offset:5168
	ds_read_b32 v24, v31 offset:2080
	global_load_dwordx2 v[56:57], v230, s[26:27]
	global_load_dword v58, v231, s[58:59]
	s_add_u32 s26, s26, 0x1000
	s_addc_u32 s27, s27, 0
	s_add_u32 s58, s58, 0x10000
	s_addc_u32 s59, s59, 0
	global_load_dwordx4 v[32:35], v232, s[34:35]
	global_load_dwordx4 v[36:39], v232, s[34:35] offset:64
	global_load_dwordx4 v[40:43], v233, s[34:35]
	global_load_dwordx4 v[44:47], v233, s[34:35] offset:64
	s_add_u32 s34, s34, 0x80
	s_addc_u32 s35, s35, 0
	ds_read_b128 v[154:157], v75 offset:0
	ds_read_b128 v[240:243], v164 offset:4096
	ds_read_b128 v[236:239], v75 offset:64
	s_waitcnt lgkmcnt(3)
	v_pk_fma_f32 v[64:65], v[8:9], v[86:87], v[118:119] op_sel:[0,0,0] op_sel_hi:[0,1,1]
	v_pk_mul_f32 v[66:67], v[16:17], v[102:103] op_sel:[0,0] op_sel_hi:[0,1]
	v_pk_fma_f32 v[64:65], v[8:9], v[88:89], v[64:65] op_sel:[1,0,0] op_sel_hi:[1,1,1]
	v_pk_fma_f32 v[66:67], v[16:17], v[104:105], v[66:67] op_sel:[1,0,0] op_sel_hi:[1,1,1]
	v_pk_fma_f32 v[64:65], v[10:11], v[90:91], v[64:65] op_sel:[0,0,0] op_sel_hi:[0,1,1]
	v_pk_fma_f32 v[66:67], v[18:19], v[106:107], v[66:67] op_sel:[0,0,0] op_sel_hi:[0,1,1]
	v_pk_fma_f32 v[64:65], v[10:11], v[92:93], v[64:65] op_sel:[1,0,0] op_sel_hi:[1,1,1]
	v_pk_fma_f32 v[66:67], v[18:19], v[108:109], v[66:67] op_sel:[1,0,0] op_sel_hi:[1,1,1]
	v_pk_fma_f32 v[64:65], v[12:13], v[94:95], v[64:65] op_sel:[0,0,0] op_sel_hi:[0,1,1]
	v_pk_fma_f32 v[66:67], v[20:21], v[110:111], v[66:67] op_sel:[0,0,0] op_sel_hi:[0,1,1]
	v_pk_fma_f32 v[64:65], v[12:13], v[96:97], v[64:65] op_sel:[1,0,0] op_sel_hi:[1,1,1]
	v_pk_fma_f32 v[66:67], v[20:21], v[112:113], v[66:67] op_sel:[1,0,0] op_sel_hi:[1,1,1]
	v_pk_fma_f32 v[64:65], v[14:15], v[98:99], v[64:65] op_sel:[0,0,0] op_sel_hi:[0,1,1]
	v_pk_fma_f32 v[66:67], v[22:23], v[114:115], v[66:67] op_sel:[0,0,0] op_sel_hi:[0,1,1]
	v_pk_fma_f32 v[64:65], v[14:15], v[100:101], v[64:65] op_sel:[1,0,0] op_sel_hi:[1,1,1]
	v_pk_fma_f32 v[66:67], v[22:23], v[116:117], v[66:67] op_sel:[1,0,0] op_sel_hi:[1,1,1]
	v_lshlrev_b32_e32 v148, 16, v24
	v_pk_add_f32 v[64:65], v[64:65], v[66:67]
	v_and_b32_e32 v149, 0xffff0000, v24
	s_waitcnt lgkmcnt(0)
	v_pk_mul_f32 v[0:1], v[0:1], v[240:241]
	v_pk_mul_f32 v[2:3], v[2:3], v[242:243]
	v_pk_mul_f32 v[4:5], v[4:5], v[240:241]
	v_pk_mul_f32 v[6:7], v[6:7], v[242:243]
	s_waitcnt vmcnt(16)
	s_nop 0
	v_mfma_f32_16x16x32_bf16 v[0:3], v[154:157], v[178:181], v[0:3]
	v_mfma_f32_16x16x32_bf16 v[4:7], v[154:157], v[186:189], v[4:7]
	v_mfma_f32_16x16x32_bf16 v[0:3], v[236:239], v[182:185], v[0:3]
	v_mfma_f32_16x16x32_bf16 v[4:7], v[236:239], v[190:193], v[4:7]
	v_mul_f32_e64 v68, |v64|, v220
	v_mul_f32_e64 v69, |v65|, v220
	v_exp_f32_e32 v68, v68
	v_exp_f32_e32 v69, v69
	v_min_f32_e32 v70, 0, v64
	v_min_f32_e32 v71, 0, v65
	v_pk_add_f32 v[68:69], v[68:69], v[222:223]
	s_nop 0
	v_log_f32_e32 v138, v68
	v_log_f32_e32 v139, v69
	s_nop 0
	v_pk_mul_f32 v[140:141], v[138:139], v[224:225]
	s_nop 0
	v_pk_fma_f32 v[142:143], v[138:139], v[224:225], v[140:141] neg_lo:[0,0,1] neg_hi:[0,0,1]
	s_nop 0
	v_pk_fma_f32 v[142:143], v[138:139], v[226:227], v[142:143]
	s_nop 0
	v_pk_fma_f32 v[142:143], v[138:139], v[224:225], v[142:143]
	s_nop 0
	v_pk_add_f32 v[144:145], v[70:71], v[142:143] neg_lo:[0,1] neg_hi:[0,1]
	s_nop 0
	v_pk_mul_f32 v[144:145], v[144:145], v[214:215]
	v_cvt_pk_bf16_f32 v244, v0, v1
	v_cvt_pk_bf16_f32 v245, v2, v3
	v_cvt_pk_bf16_f32 v246, v4, v5
	v_cvt_pk_bf16_f32 v247, v6, v7
	global_store_dwordx2 v234, v[244:245], s[100:101]
	global_store_dwordx2 v235, v[246:247], s[100:101]
	s_add_u32 s100, s100, 0x40000
	s_addc_u32 s101, s101, 0
	v_add_f32_dpp v144, v144, v144 row_shr:1 row_mask:0xf bank_mask:0xf
	v_add_f32_dpp v145, v145, v145 row_shr:1 row_mask:0xf bank_mask:0xf
	s_nop 0
	v_add_f32_dpp v144, v144, v144 row_shr:2 row_mask:0xf bank_mask:0xf
	v_add_f32_dpp v145, v145, v145 row_shr:2 row_mask:0xf bank_mask:0xf
	s_nop 0
	v_add_f32_dpp v144, v144, v144 row_shr:4 row_mask:0xf bank_mask:0xf
	v_add_f32_dpp v145, v145, v145 row_shr:4 row_mask:0xf bank_mask:0xf
	s_nop 0
	v_add_f32_dpp v144, v144, v144 row_shr:8 row_mask:0xf bank_mask:0xf
	v_add_f32_dpp v145, v145, v145 row_shr:8 row_mask:0xf bank_mask:0xf
	s_nop 0
	v_add_f32_dpp v144, v144, v144 row_bcast:15 row_mask:0xa bank_mask:0xf
	v_add_f32_dpp v145, v145, v145 row_bcast:15 row_mask:0xa bank_mask:0xf
	s_nop 0
	v_add_f32_dpp v144, v144, v144 row_bcast:31 row_mask:0xc bank_mask:0xf
	v_add_f32_dpp v145, v145, v145 row_bcast:31 row_mask:0xc bank_mask:0xf
	s_nop 0
	v_readlane_b32 s98, v144, 63
	v_readlane_b32 s99, v145, 63
	s_nop 1
	v_pk_add_f32 v[146:147], s[98:99], v[144:145] neg_lo:[0,1] neg_hi:[0,1]
	v_mul_f32_e64 v152, s98, v228
	v_mul_f32_e64 v153, s99, v228
	v_pk_mul_f32 v[146:147], v[146:147], v[228:229]
	v_exp_f32_e32 v152, v152
	v_exp_f32_e32 v153, v153
	v_exp_f32_e32 v146, v146
	v_exp_f32_e32 v147, v147
	s_nop 0
	v_pk_mul_f32 v[146:147], v[146:147], v[148:149]
	s_nop 0
	v_cvt_pk_bf16_f32 v150, v146, v147
	s_nop 0
	ds_write_b16 v172, v150 offset:2048
	ds_write_b16_d16_hi v172, v150 offset:2176
	s_and_saveexec_b64 s[20:21], vcc
	ds_write_b64 v163, v[152:153] offset:4160
	s_mov_b64 exec, s[20:21]
	s_waitcnt vmcnt(22)
	ds_write_b64 v28, v[48:49] offset:0
	ds_write_b32 v30, v50 offset:0
	s_waitcnt lgkmcnt(0)
	s_barrier
	ds_read_b128 v[8:11], v29 offset:0
	ds_read_b128 v[12:15], v29 offset:16
	ds_read_b128 v[16:19], v29 offset:32
	ds_read_b128 v[20:23], v29 offset:48
	ds_read_b32 v24, v31 offset:0
	s_sub_u32 s28, s28, 1
	s_cmp_lg_u32 s28, 0
	s_cbranch_scc1 .Lgscan_loop
; #define MFMA16(a, b, c) __builtin_amdgcn_mfma_f32_16x16x32_bf16((a), (b), (c), 0, 0, 0)
;     ...
;         for (int n = 0; n < 64; ++n) {
;             const int buf = n & 1;
;             f32x4 a4[4]; bf16x8 vfr[2][2];
; #pragma unroll
;             for (int q = 0; q < 4; ++q) a4[q] = a4n[q];
;             const unsigned kraw = krawn;
; #pragma unroll
;             for (int e = 0; e < 2; ++e)
; #pragma unroll
;                 for (int ks = 0; ks < 2; ++ks) vfr[e][ks] = vfrn[e][ks];
;             if (n + 1 < 64) ldchunk(n + 1);
;             float cum[2];
; #pragma unroll
;             for (int e = 0; e < 2; ++e) {
;                 float z = bb[e];
; #pragma unroll
;                 for (int q = 0; q < 4; ++q) { z += a4[q].x * wa[e][4 * q] + a4[q].y * wa[e][4 * q + 1] + a4[q].z * wa[e][4 * q + 2] + a4[q].w * wa[e][4 * q + 3]; }
;                 cum[e] = (fminf(z, 0.f) - __logf(1.f + __expf(-fabsf(z)))) * (1.f / 16.f);
;             }
; #pragma unroll
;             for (int o = 1; o < 64; o <<= 1) {
;                 const float t0 = __shfl_up(cum[0], o), t1 = __shfl_up(cum[1], o);
;                 if (l >= o) { cum[0] += t0; cum[1] += t1; }
;             }
;             const float tot0 = __shfl(cum[0], 63), tot1 = __shfl(cum[1], 63);
;             kdl[(buf * 16 + 2 * w) * 64 + l] = f2bf(bf2f(kraw & 0xffffu) * __expf(tot0 - cum[0]));
;             kdl[(buf * 16 + 2 * w + 1) * 64 + l] = f2bf(bf2f(kraw >> 16) * __expf(tot1 - cum[1]));
;             if (l == 0) { decl[buf * 16 + 2 * w] = __expf(tot0); decl[buf * 16 + 2 * w + 1] = __expf(tot1); }
;             __syncthreads();
;             const f32x4 d4 = *(const f32x4*)(decl + buf * 16 + (l >> 4) * 4);
; #pragma unroll
;             for (int e = 0; e < 2; ++e) acc[e] = acc[e] * d4;
; #pragma unroll
;             for (int ks = 0; ks < 2; ++ks) {
;                 const bf16x8 af = *(const bf16x8*)(kdl + (buf * 16 + (l & 15)) * 64 + ks * 32 + (l >> 4) * 8);
; #pragma unroll
;                 for (int e = 0; e < 2; ++e) acc[e] = MFMA16(af, vfr[e][ks], acc[e]);
;             }
;             const int cidx = b * 64 + n;
; #pragma unroll
;             for (int e = 0; e < 2; ++e) {
;                 const int vv = (2 * w + e) * 16 + (l & 15);
;                 *(u32x2*)(ST + (((size_t)(cidx * 4 + hh)) * 256 + vv) * 128 + ksl * 16 + (l >> 4) * 4) = pk4(acc[e].x, acc[e].y, acc[e].z, acc[e].w);
;             }
	global_load_dwordx2 v[48:49], v230, s[26:27]
	global_load_dword v50, v231, s[58:59]
	s_add_u32 s26, s26, 0x1000
	s_addc_u32 s27, s27, 0
	s_add_u32 s58, s58, 0x10000
	s_addc_u32 s59, s59, 0
	global_load_dwordx4 v[178:181], v232, s[34:35]
	global_load_dwordx4 v[182:185], v232, s[34:35] offset:64
	global_load_dwordx4 v[186:189], v233, s[34:35]
	global_load_dwordx4 v[190:193], v233, s[34:35] offset:64
	s_add_u32 s34, s34, 0x80
	s_addc_u32 s35, s35, 0
	ds_read_b128 v[154:157], v75 offset:2048
	ds_read_b128 v[240:243], v164 offset:4160
	ds_read_b128 v[236:239], v75 offset:2112
	s_waitcnt lgkmcnt(3)
	v_pk_fma_f32 v[64:65], v[8:9], v[86:87], v[118:119] op_sel:[0,0,0] op_sel_hi:[0,1,1]
	v_pk_mul_f32 v[66:67], v[16:17], v[102:103] op_sel:[0,0] op_sel_hi:[0,1]
	v_pk_fma_f32 v[64:65], v[8:9], v[88:89], v[64:65] op_sel:[1,0,0] op_sel_hi:[1,1,1]
	v_pk_fma_f32 v[66:67], v[16:17], v[104:105], v[66:67] op_sel:[1,0,0] op_sel_hi:[1,1,1]
	v_pk_fma_f32 v[64:65], v[10:11], v[90:91], v[64:65] op_sel:[0,0,0] op_sel_hi:[0,1,1]
	v_pk_fma_f32 v[66:67], v[18:19], v[106:107], v[66:67] op_sel:[0,0,0] op_sel_hi:[0,1,1]
	v_pk_fma_f32 v[64:65], v[10:11], v[92:93], v[64:65] op_sel:[1,0,0] op_sel_hi:[1,1,1]
	v_pk_fma_f32 v[66:67], v[18:19], v[108:109], v[66:67] op_sel:[1,0,0] op_sel_hi:[1,1,1]
	v_pk_fma_f32 v[64:65], v[12:13], v[94:95], v[64:65] op_sel:[0,0,0] op_sel_hi:[0,1,1]
	v_pk_fma_f32 v[66:67], v[20:21], v[110:111], v[66:67] op_sel:[0,0,0] op_sel_hi:[0,1,1]
	v_pk_fma_f32 v[64:65], v[12:13], v[96:97], v[64:65] op_sel:[1,0,0] op_sel_hi:[1,1,1]
	v_pk_fma_f32 v[66:67], v[20:21], v[112:113], v[66:67] op_sel:[1,0,0] op_sel_hi:[1,1,1]
	v_pk_fma_f32 v[64:65], v[14:15], v[98:99], v[64:65] op_sel:[0,0,0] op_sel_hi:[0,1,1]
	v_pk_fma_f32 v[66:67], v[22:23], v[114:115], v[66:67] op_sel:[0,0,0] op_sel_hi:[0,1,1]
	v_pk_fma_f32 v[64:65], v[14:15], v[100:101], v[64:65] op_sel:[1,0,0] op_sel_hi:[1,1,1]
	v_pk_fma_f32 v[66:67], v[22:23], v[116:117], v[66:67] op_sel:[1,0,0] op_sel_hi:[1,1,1]
	v_lshlrev_b32_e32 v148, 16, v24
	v_pk_add_f32 v[64:65], v[64:65], v[66:67]
	v_and_b32_e32 v149, 0xffff0000, v24
	s_waitcnt lgkmcnt(0)
	v_pk_mul_f32 v[0:1], v[0:1], v[240:241]
	v_pk_mul_f32 v[2:3], v[2:3], v[242:243]
	v_pk_mul_f32 v[4:5], v[4:5], v[240:241]
	v_pk_mul_f32 v[6:7], v[6:7], v[242:243]
	s_waitcnt vmcnt(16)
	s_nop 0
	v_mfma_f32_16x16x32_bf16 v[0:3], v[154:157], v[194:197], v[0:3]
	v_mfma_f32_16x16x32_bf16 v[4:7], v[154:157], v[202:205], v[4:7]
	v_mfma_f32_16x16x32_bf16 v[0:3], v[236:239], v[198:201], v[0:3]
	v_mfma_f32_16x16x32_bf16 v[4:7], v[236:239], v[206:209], v[4:7]
	v_mul_f32_e64 v68, |v64|, v220
	v_mul_f32_e64 v69, |v65|, v220
	v_exp_f32_e32 v68, v68
	v_exp_f32_e32 v69, v69
	v_min_f32_e32 v70, 0, v64
	v_min_f32_e32 v71, 0, v65
	v_pk_add_f32 v[68:69], v[68:69], v[222:223]
	s_nop 0
	v_log_f32_e32 v138, v68
	v_log_f32_e32 v139, v69
	s_nop 0
	v_pk_mul_f32 v[140:141], v[138:139], v[224:225]
	s_nop 0
	v_pk_fma_f32 v[142:143], v[138:139], v[224:225], v[140:141] neg_lo:[0,0,1] neg_hi:[0,0,1]
	s_nop 0
	v_pk_fma_f32 v[142:143], v[138:139], v[226:227], v[142:143]
	s_nop 0
	v_pk_fma_f32 v[142:143], v[138:139], v[224:225], v[142:143]
	s_nop 0
	v_pk_add_f32 v[144:145], v[70:71], v[142:143] neg_lo:[0,1] neg_hi:[0,1]
	s_nop 0
	v_pk_mul_f32 v[144:145], v[144:145], v[214:215]
	v_cvt_pk_bf16_f32 v244, v0, v1
	v_cvt_pk_bf16_f32 v245, v2, v3
	v_cvt_pk_bf16_f32 v246, v4, v5
	v_cvt_pk_bf16_f32 v247, v6, v7
	global_store_dwordx2 v234, v[244:245], s[100:101]
	global_store_dwordx2 v235, v[246:247], s[100:101]
	s_add_u32 s100, s100, 0x40000
	s_addc_u32 s101, s101, 0
	v_add_f32_dpp v144, v144, v144 row_shr:1 row_mask:0xf bank_mask:0xf
	v_add_f32_dpp v145, v145, v145 row_shr:1 row_mask:0xf bank_mask:0xf
	s_nop 0
	v_add_f32_dpp v144, v144, v144 row_shr:2 row_mask:0xf bank_mask:0xf
	v_add_f32_dpp v145, v145, v145 row_shr:2 row_mask:0xf bank_mask:0xf
	s_nop 0
	v_add_f32_dpp v144, v144, v144 row_shr:4 row_mask:0xf bank_mask:0xf
	v_add_f32_dpp v145, v145, v145 row_shr:4 row_mask:0xf bank_mask:0xf
	s_nop 0
	v_add_f32_dpp v144, v144, v144 row_shr:8 row_mask:0xf bank_mask:0xf
	v_add_f32_dpp v145, v145, v145 row_shr:8 row_mask:0xf bank_mask:0xf
	s_nop 0
	v_add_f32_dpp v144, v144, v144 row_bcast:15 row_mask:0xa bank_mask:0xf
	v_add_f32_dpp v145, v145, v145 row_bcast:15 row_mask:0xa bank_mask:0xf
	s_nop 0
	v_add_f32_dpp v144, v144, v144 row_bcast:31 row_mask:0xc bank_mask:0xf
	v_add_f32_dpp v145, v145, v145 row_bcast:31 row_mask:0xc bank_mask:0xf
	s_nop 0
	v_readlane_b32 s98, v144, 63
	v_readlane_b32 s99, v145, 63
	s_nop 1
	v_pk_add_f32 v[146:147], s[98:99], v[144:145] neg_lo:[0,1] neg_hi:[0,1]
	v_mul_f32_e64 v152, s98, v228
	v_mul_f32_e64 v153, s99, v228
	v_pk_mul_f32 v[146:147], v[146:147], v[228:229]
	v_exp_f32_e32 v152, v152
	v_exp_f32_e32 v153, v153
	v_exp_f32_e32 v146, v146
	v_exp_f32_e32 v147, v147
	s_nop 0
	v_pk_mul_f32 v[146:147], v[146:147], v[148:149]
	s_nop 0
	v_cvt_pk_bf16_f32 v150, v146, v147
	s_nop 0
	ds_write_b16 v172, v150 offset:0
	ds_write_b16_d16_hi v172, v150 offset:128
	s_and_saveexec_b64 s[20:21], vcc
	ds_write_b64 v163, v[152:153] offset:4096
	s_mov_b64 exec, s[20:21]
	s_waitcnt vmcnt(22)
	ds_write_b64 v28, v[52:53] offset:5120
	ds_write_b32 v30, v54 offset:2080
	s_waitcnt lgkmcnt(0)
	s_barrier
; #define MFMA16(a, b, c) __builtin_amdgcn_mfma_f32_16x16x32_bf16((a), (b), (c), 0, 0, 0)
;     ...
;         for (int n = 0; n < 64; ++n) {
;             const int buf = n & 1;
;             f32x4 a4[4]; bf16x8 vfr[2][2];
; #pragma unroll
;             for (int q = 0; q < 4; ++q) a4[q] = a4n[q];
;             const unsigned kraw = krawn;
; #pragma unroll
;             for (int e = 0; e < 2; ++e)
; #pragma unroll
;                 for (int ks = 0; ks < 2; ++ks) vfr[e][ks] = vfrn[e][ks];
;             if (n + 1 < 64) ldchunk(n + 1);
;             float cum[2];
; #pragma unroll
;             for (int e = 0; e < 2; ++e) {
;                 float z = bb[e];
; #pragma unroll
;                 for (int q = 0; q < 4; ++q) { z += a4[q].x * wa[e][4 * q] + a4[q].y * wa[e][4 * q + 1] + a4[q].z * wa[e][4 * q + 2] + a4[q].w * wa[e][4 * q + 3]; }
;                 cum[e] = (fminf(z, 0.f) - __logf(1.f + __expf(-fabsf(z)))) * (1.f / 16.f);
;             }
; #pragma unroll
;             for (int o = 1; o < 64; o <<= 1) {
;                 const float t0 = __shfl_up(cum[0], o), t1 = __shfl_up(cum[1], o);
;                 if (l >= o) { cum[0] += t0; cum[1] += t1; }
;             }
;             const float tot0 = __shfl(cum[0], 63), tot1 = __shfl(cum[1], 63);
;             kdl[(buf * 16 + 2 * w) * 64 + l] = f2bf(bf2f(kraw & 0xffffu) * __expf(tot0 - cum[0]));
;             kdl[(buf * 16 + 2 * w + 1) * 64 + l] = f2bf(bf2f(kraw >> 16) * __expf(tot1 - cum[1]));
;             if (l == 0) { decl[buf * 16 + 2 * w] = __expf(tot0); decl[buf * 16 + 2 * w + 1] = __expf(tot1); }
;             __syncthreads();
;             const f32x4 d4 = *(const f32x4*)(decl + buf * 16 + (l >> 4) * 4);
; #pragma unroll
;             for (int e = 0; e < 2; ++e) acc[e] = acc[e] * d4;
; #pragma unroll
;             for (int ks = 0; ks < 2; ++ks) {
;                 const bf16x8 af = *(const bf16x8*)(kdl + (buf * 16 + (l & 15)) * 64 + ks * 32 + (l >> 4) * 8);
; #pragma unroll
;                 for (int e = 0; e < 2; ++e) acc[e] = MFMA16(af, vfr[e][ks], acc[e]);
;             }
;             const int cidx = b * 64 + n;
; #pragma unroll
;             for (int e = 0; e < 2; ++e) {
;                 const int vv = (2 * w + e) * 16 + (l & 15);
;                 *(u32x2*)(ST + (((size_t)(cidx * 4 + hh)) * 256 + vv) * 128 + ksl * 16 + (l >> 4) * 4) = pk4(acc[e].x, acc[e].y, acc[e].z, acc[e].w);
;             }
	ds_read_b128 v[8:11], v29 offset:5120
	ds_read_b128 v[12:15], v29 offset:5136
	ds_read_b128 v[16:19], v29 offset:5152
	ds_read_b128 v[20:23], v29 offset:5168
	ds_read_b32 v24, v31 offset:2080
	global_load_dwordx4 v[194:197], v232, s[34:35]
	global_load_dwordx4 v[198:201], v232, s[34:35] offset:64
	global_load_dwordx4 v[202:205], v233, s[34:35]
	global_load_dwordx4 v[206:209], v233, s[34:35] offset:64
	s_add_u32 s34, s34, 0x80
	s_addc_u32 s35, s35, 0
	ds_read_b128 v[154:157], v75 offset:0
	ds_read_b128 v[240:243], v164 offset:4096
	ds_read_b128 v[236:239], v75 offset:64
	s_waitcnt lgkmcnt(3)
	v_pk_fma_f32 v[64:65], v[8:9], v[86:87], v[118:119] op_sel:[0,0,0] op_sel_hi:[0,1,1]
	v_pk_mul_f32 v[66:67], v[16:17], v[102:103] op_sel:[0,0] op_sel_hi:[0,1]
	v_pk_fma_f32 v[64:65], v[8:9], v[88:89], v[64:65] op_sel:[1,0,0] op_sel_hi:[1,1,1]
	v_pk_fma_f32 v[66:67], v[16:17], v[104:105], v[66:67] op_sel:[1,0,0] op_sel_hi:[1,1,1]
	v_pk_fma_f32 v[64:65], v[10:11], v[90:91], v[64:65] op_sel:[0,0,0] op_sel_hi:[0,1,1]
	v_pk_fma_f32 v[66:67], v[18:19], v[106:107], v[66:67] op_sel:[0,0,0] op_sel_hi:[0,1,1]
	v_pk_fma_f32 v[64:65], v[10:11], v[92:93], v[64:65] op_sel:[1,0,0] op_sel_hi:[1,1,1]
	v_pk_fma_f32 v[66:67], v[18:19], v[108:109], v[66:67] op_sel:[1,0,0] op_sel_hi:[1,1,1]
	v_pk_fma_f32 v[64:65], v[12:13], v[94:95], v[64:65] op_sel:[0,0,0] op_sel_hi:[0,1,1]
	v_pk_fma_f32 v[66:67], v[20:21], v[110:111], v[66:67] op_sel:[0,0,0] op_sel_hi:[0,1,1]
	v_pk_fma_f32 v[64:65], v[12:13], v[96:97], v[64:65] op_sel:[1,0,0] op_sel_hi:[1,1,1]
	v_pk_fma_f32 v[66:67], v[20:21], v[112:113], v[66:67] op_sel:[1,0,0] op_sel_hi:[1,1,1]
	v_pk_fma_f32 v[64:65], v[14:15], v[98:99], v[64:65] op_sel:[0,0,0] op_sel_hi:[0,1,1]
	v_pk_fma_f32 v[66:67], v[22:23], v[114:115], v[66:67] op_sel:[0,0,0] op_sel_hi:[0,1,1]
	v_pk_fma_f32 v[64:65], v[14:15], v[100:101], v[64:65] op_sel:[1,0,0] op_sel_hi:[1,1,1]
	v_pk_fma_f32 v[66:67], v[22:23], v[116:117], v[66:67] op_sel:[1,0,0] op_sel_hi:[1,1,1]
	v_lshlrev_b32_e32 v148, 16, v24
	v_pk_add_f32 v[64:65], v[64:65], v[66:67]
	v_and_b32_e32 v149, 0xffff0000, v24
	s_waitcnt lgkmcnt(0)
	v_pk_mul_f32 v[0:1], v[0:1], v[240:241]
	v_pk_mul_f32 v[2:3], v[2:3], v[242:243]
	v_pk_mul_f32 v[4:5], v[4:5], v[240:241]
	v_pk_mul_f32 v[6:7], v[6:7], v[242:243]
	s_waitcnt vmcnt(14)
	s_nop 0
	v_mfma_f32_16x16x32_bf16 v[0:3], v[154:157], v[32:35], v[0:3]
	v_mfma_f32_16x16x32_bf16 v[4:7], v[154:157], v[40:43], v[4:7]
	v_mfma_f32_16x16x32_bf16 v[0:3], v[236:239], v[36:39], v[0:3]
	v_mfma_f32_16x16x32_bf16 v[4:7], v[236:239], v[44:47], v[4:7]
	v_mul_f32_e64 v68, |v64|, v220
	v_mul_f32_e64 v69, |v65|, v220
	v_exp_f32_e32 v68, v68
	v_exp_f32_e32 v69, v69
	v_min_f32_e32 v70, 0, v64
	v_min_f32_e32 v71, 0, v65
	v_pk_add_f32 v[68:69], v[68:69], v[222:223]
	s_nop 0
	v_log_f32_e32 v138, v68
	v_log_f32_e32 v139, v69
	s_nop 0
	v_pk_mul_f32 v[140:141], v[138:139], v[224:225]
	s_nop 0
	v_pk_fma_f32 v[142:143], v[138:139], v[224:225], v[140:141] neg_lo:[0,0,1] neg_hi:[0,0,1]
	s_nop 0
	v_pk_fma_f32 v[142:143], v[138:139], v[226:227], v[142:143]
	s_nop 0
	v_pk_fma_f32 v[142:143], v[138:139], v[224:225], v[142:143]
	s_nop 0
	v_pk_add_f32 v[144:145], v[70:71], v[142:143] neg_lo:[0,1] neg_hi:[0,1]
	s_nop 0
	v_pk_mul_f32 v[144:145], v[144:145], v[214:215]
	v_cvt_pk_bf16_f32 v244, v0, v1
	v_cvt_pk_bf16_f32 v245, v2, v3
	v_cvt_pk_bf16_f32 v246, v4, v5
	v_cvt_pk_bf16_f32 v247, v6, v7
	global_store_dwordx2 v234, v[244:245], s[100:101]
	global_store_dwordx2 v235, v[246:247], s[100:101]
	s_add_u32 s100, s100, 0x40000
	s_addc_u32 s101, s101, 0
	v_add_f32_dpp v144, v144, v144 row_shr:1 row_mask:0xf bank_mask:0xf
	v_add_f32_dpp v145, v145, v145 row_shr:1 row_mask:0xf bank_mask:0xf
	s_nop 0
	v_add_f32_dpp v144, v144, v144 row_shr:2 row_mask:0xf bank_mask:0xf
	v_add_f32_dpp v145, v145, v145 row_shr:2 row_mask:0xf bank_mask:0xf
	s_nop 0
	v_add_f32_dpp v144, v144, v144 row_shr:4 row_mask:0xf bank_mask:0xf
	v_add_f32_dpp v145, v145, v145 row_shr:4 row_mask:0xf bank_mask:0xf
	s_nop 0
	v_add_f32_dpp v144, v144, v144 row_shr:8 row_mask:0xf bank_mask:0xf
	v_add_f32_dpp v145, v145, v145 row_shr:8 row_mask:0xf bank_mask:0xf
	s_nop 0
	v_add_f32_dpp v144, v144, v144 row_bcast:15 row_mask:0xa bank_mask:0xf
	v_add_f32_dpp v145, v145, v145 row_bcast:15 row_mask:0xa bank_mask:0xf
	s_nop 0
	v_add_f32_dpp v144, v144, v144 row_bcast:31 row_mask:0xc bank_mask:0xf
	v_add_f32_dpp v145, v145, v145 row_bcast:31 row_mask:0xc bank_mask:0xf
	s_nop 0
	v_readlane_b32 s98, v144, 63
	v_readlane_b32 s99, v145, 63
	s_nop 1
	v_pk_add_f32 v[146:147], s[98:99], v[144:145] neg_lo:[0,1] neg_hi:[0,1]
	v_mul_f32_e64 v152, s98, v228
	v_mul_f32_e64 v153, s99, v228
	v_pk_mul_f32 v[146:147], v[146:147], v[228:229]
	v_exp_f32_e32 v152, v152
	v_exp_f32_e32 v153, v153
	v_exp_f32_e32 v146, v146
	v_exp_f32_e32 v147, v147
	s_nop 0
	v_pk_mul_f32 v[146:147], v[146:147], v[148:149]
	s_nop 0
	v_cvt_pk_bf16_f32 v150, v146, v147
	s_nop 0
	ds_write_b16 v172, v150 offset:2048
	ds_write_b16_d16_hi v172, v150 offset:2176
	s_and_saveexec_b64 s[20:21], vcc
	ds_write_b64 v163, v[152:153] offset:4160
	s_mov_b64 exec, s[20:21]
	s_waitcnt vmcnt(20)
	ds_write_b64 v28, v[56:57] offset:0
	ds_write_b32 v30, v58 offset:0
	s_waitcnt lgkmcnt(0)
	s_barrier
; #define MFMA16(a, b, c) __builtin_amdgcn_mfma_f32_16x16x32_bf16((a), (b), (c), 0, 0, 0)
;     ...
;         for (int n = 0; n < 64; ++n) {
;             const int buf = n & 1;
;             f32x4 a4[4]; bf16x8 vfr[2][2];
; #pragma unroll
;             for (int q = 0; q < 4; ++q) a4[q] = a4n[q];
;             const unsigned kraw = krawn;
; #pragma unroll
;             for (int e = 0; e < 2; ++e)
; #pragma unroll
;                 for (int ks = 0; ks < 2; ++ks) vfr[e][ks] = vfrn[e][ks];
;             if (n + 1 < 64) ldchunk(n + 1);
;             float cum[2];
; #pragma unroll
;             for (int e = 0; e < 2; ++e) {
;                 float z = bb[e];
; #pragma unroll
;                 for (int q = 0; q < 4; ++q) { z += a4[q].x * wa[e][4 * q] + a4[q].y * wa[e][4 * q + 1] + a4[q].z * wa[e][4 * q + 2] + a4[q].w * wa[e][4 * q + 3]; }
;                 cum[e] = (fminf(z, 0.f) - __logf(1.f + __expf(-fabsf(z)))) * (1.f / 16.f);
;             }
; #pragma unroll
;             for (int o = 1; o < 64; o <<= 1) {
;                 const float t0 = __shfl_up(cum[0], o), t1 = __shfl_up(cum[1], o);
;                 if (l >= o) { cum[0] += t0; cum[1] += t1; }
;             }
;             const float tot0 = __shfl(cum[0], 63), tot1 = __shfl(cum[1], 63);
;             kdl[(buf * 16 + 2 * w) * 64 + l] = f2bf(bf2f(kraw & 0xffffu) * __expf(tot0 - cum[0]));
;             kdl[(buf * 16 + 2 * w + 1) * 64 + l] = f2bf(bf2f(kraw >> 16) * __expf(tot1 - cum[1]));
;             if (l == 0) { decl[buf * 16 + 2 * w] = __expf(tot0); decl[buf * 16 + 2 * w + 1] = __expf(tot1); }
;             __syncthreads();
;             const f32x4 d4 = *(const f32x4*)(decl + buf * 16 + (l >> 4) * 4);
; #pragma unroll
;             for (int e = 0; e < 2; ++e) acc[e] = acc[e] * d4;
; #pragma unroll
;             for (int ks = 0; ks < 2; ++ks) {
;                 const bf16x8 af = *(const bf16x8*)(kdl + (buf * 16 + (l & 15)) * 64 + ks * 32 + (l >> 4) * 8);
; #pragma unroll
;                 for (int e = 0; e < 2; ++e) acc[e] = MFMA16(af, vfr[e][ks], acc[e]);
;             }
;             const int cidx = b * 64 + n;
; #pragma unroll
;             for (int e = 0; e < 2; ++e) {
;                 const int vv = (2 * w + e) * 16 + (l & 15);
;                 *(u32x2*)(ST + (((size_t)(cidx * 4 + hh)) * 256 + vv) * 128 + ksl * 16 + (l >> 4) * 4) = pk4(acc[e].x, acc[e].y, acc[e].z, acc[e].w);
;             }
	ds_read_b128 v[8:11], v29 offset:0
	ds_read_b128 v[12:15], v29 offset:16
	ds_read_b128 v[16:19], v29 offset:32
	ds_read_b128 v[20:23], v29 offset:48
	ds_read_b32 v24, v31 offset:0
	global_load_dwordx4 v[32:35], v232, s[34:35]
	global_load_dwordx4 v[36:39], v232, s[34:35] offset:64
	global_load_dwordx4 v[40:43], v233, s[34:35]
	global_load_dwordx4 v[44:47], v233, s[34:35] offset:64
	s_add_u32 s34, s34, 0x80
	s_addc_u32 s35, s35, 0
	ds_read_b128 v[154:157], v75 offset:2048
	ds_read_b128 v[240:243], v164 offset:4160
	ds_read_b128 v[236:239], v75 offset:2112
	s_waitcnt lgkmcnt(3)
	v_pk_fma_f32 v[64:65], v[8:9], v[86:87], v[118:119] op_sel:[0,0,0] op_sel_hi:[0,1,1]
	v_pk_mul_f32 v[66:67], v[16:17], v[102:103] op_sel:[0,0] op_sel_hi:[0,1]
	v_pk_fma_f32 v[64:65], v[8:9], v[88:89], v[64:65] op_sel:[1,0,0] op_sel_hi:[1,1,1]
	v_pk_fma_f32 v[66:67], v[16:17], v[104:105], v[66:67] op_sel:[1,0,0] op_sel_hi:[1,1,1]
	v_pk_fma_f32 v[64:65], v[10:11], v[90:91], v[64:65] op_sel:[0,0,0] op_sel_hi:[0,1,1]
	v_pk_fma_f32 v[66:67], v[18:19], v[106:107], v[66:67] op_sel:[0,0,0] op_sel_hi:[0,1,1]
	v_pk_fma_f32 v[64:65], v[10:11], v[92:93], v[64:65] op_sel:[1,0,0] op_sel_hi:[1,1,1]
	v_pk_fma_f32 v[66:67], v[18:19], v[108:109], v[66:67] op_sel:[1,0,0] op_sel_hi:[1,1,1]
	v_pk_fma_f32 v[64:65], v[12:13], v[94:95], v[64:65] op_sel:[0,0,0] op_sel_hi:[0,1,1]
	v_pk_fma_f32 v[66:67], v[20:21], v[110:111], v[66:67] op_sel:[0,0,0] op_sel_hi:[0,1,1]
	v_pk_fma_f32 v[64:65], v[12:13], v[96:97], v[64:65] op_sel:[1,0,0] op_sel_hi:[1,1,1]
	v_pk_fma_f32 v[66:67], v[20:21], v[112:113], v[66:67] op_sel:[1,0,0] op_sel_hi:[1,1,1]
	v_pk_fma_f32 v[64:65], v[14:15], v[98:99], v[64:65] op_sel:[0,0,0] op_sel_hi:[0,1,1]
	v_pk_fma_f32 v[66:67], v[22:23], v[114:115], v[66:67] op_sel:[0,0,0] op_sel_hi:[0,1,1]
	v_pk_fma_f32 v[64:65], v[14:15], v[100:101], v[64:65] op_sel:[1,0,0] op_sel_hi:[1,1,1]
	v_pk_fma_f32 v[66:67], v[22:23], v[116:117], v[66:67] op_sel:[1,0,0] op_sel_hi:[1,1,1]
	v_lshlrev_b32_e32 v148, 16, v24
	v_pk_add_f32 v[64:65], v[64:65], v[66:67]
	v_and_b32_e32 v149, 0xffff0000, v24
	s_waitcnt lgkmcnt(0)
	v_pk_mul_f32 v[0:1], v[0:1], v[240:241]
	v_pk_mul_f32 v[2:3], v[2:3], v[242:243]
	v_pk_mul_f32 v[4:5], v[4:5], v[240:241]
	v_pk_mul_f32 v[6:7], v[6:7], v[242:243]
	s_waitcnt vmcnt(12)
	s_nop 0
	v_mfma_f32_16x16x32_bf16 v[0:3], v[154:157], v[178:181], v[0:3]
	v_mfma_f32_16x16x32_bf16 v[4:7], v[154:157], v[186:189], v[4:7]
	v_mfma_f32_16x16x32_bf16 v[0:3], v[236:239], v[182:185], v[0:3]
	v_mfma_f32_16x16x32_bf16 v[4:7], v[236:239], v[190:193], v[4:7]
	v_mul_f32_e64 v68, |v64|, v220
	v_mul_f32_e64 v69, |v65|, v220
	v_exp_f32_e32 v68, v68
	v_exp_f32_e32 v69, v69
	v_min_f32_e32 v70, 0, v64
	v_min_f32_e32 v71, 0, v65
	v_pk_add_f32 v[68:69], v[68:69], v[222:223]
	s_nop 0
	v_log_f32_e32 v138, v68
	v_log_f32_e32 v139, v69
	s_nop 0
	v_pk_mul_f32 v[140:141], v[138:139], v[224:225]
	s_nop 0
	v_pk_fma_f32 v[142:143], v[138:139], v[224:225], v[140:141] neg_lo:[0,0,1] neg_hi:[0,0,1]
	s_nop 0
	v_pk_fma_f32 v[142:143], v[138:139], v[226:227], v[142:143]
	s_nop 0
	v_pk_fma_f32 v[142:143], v[138:139], v[224:225], v[142:143]
	s_nop 0
	v_pk_add_f32 v[144:145], v[70:71], v[142:143] neg_lo:[0,1] neg_hi:[0,1]
	s_nop 0
	v_pk_mul_f32 v[144:145], v[144:145], v[214:215]
	v_cvt_pk_bf16_f32 v244, v0, v1
	v_cvt_pk_bf16_f32 v245, v2, v3
	v_cvt_pk_bf16_f32 v246, v4, v5
	v_cvt_pk_bf16_f32 v247, v6, v7
	global_store_dwordx2 v234, v[244:245], s[100:101]
	global_store_dwordx2 v235, v[246:247], s[100:101]
	s_add_u32 s100, s100, 0x40000
	s_addc_u32 s101, s101, 0
	v_add_f32_dpp v144, v144, v144 row_shr:1 row_mask:0xf bank_mask:0xf
	v_add_f32_dpp v145, v145, v145 row_shr:1 row_mask:0xf bank_mask:0xf
	s_nop 0
	v_add_f32_dpp v144, v144, v144 row_shr:2 row_mask:0xf bank_mask:0xf
	v_add_f32_dpp v145, v145, v145 row_shr:2 row_mask:0xf bank_mask:0xf
	s_nop 0
	v_add_f32_dpp v144, v144, v144 row_shr:4 row_mask:0xf bank_mask:0xf
	v_add_f32_dpp v145, v145, v145 row_shr:4 row_mask:0xf bank_mask:0xf
	s_nop 0
	v_add_f32_dpp v144, v144, v144 row_shr:8 row_mask:0xf bank_mask:0xf
	v_add_f32_dpp v145, v145, v145 row_shr:8 row_mask:0xf bank_mask:0xf
	s_nop 0
	v_add_f32_dpp v144, v144, v144 row_bcast:15 row_mask:0xa bank_mask:0xf
	v_add_f32_dpp v145, v145, v145 row_bcast:15 row_mask:0xa bank_mask:0xf
	s_nop 0
	v_add_f32_dpp v144, v144, v144 row_bcast:31 row_mask:0xc bank_mask:0xf
	v_add_f32_dpp v145, v145, v145 row_bcast:31 row_mask:0xc bank_mask:0xf
	s_nop 0
	v_readlane_b32 s98, v144, 63
	v_readlane_b32 s99, v145, 63
	s_nop 1
	v_pk_add_f32 v[146:147], s[98:99], v[144:145] neg_lo:[0,1] neg_hi:[0,1]
	v_mul_f32_e64 v152, s98, v228
	v_mul_f32_e64 v153, s99, v228
	v_pk_mul_f32 v[146:147], v[146:147], v[228:229]
	v_exp_f32_e32 v152, v152
	v_exp_f32_e32 v153, v153
	v_exp_f32_e32 v146, v146
	v_exp_f32_e32 v147, v147
	s_nop 0
	v_pk_mul_f32 v[146:147], v[146:147], v[148:149]
	s_nop 0
	v_cvt_pk_bf16_f32 v150, v146, v147
	s_nop 0
	ds_write_b16 v172, v150 offset:0
	ds_write_b16_d16_hi v172, v150 offset:128
	s_and_saveexec_b64 s[20:21], vcc
	ds_write_b64 v163, v[152:153] offset:4096
	s_mov_b64 exec, s[20:21]
	s_waitcnt vmcnt(18)
	ds_write_b64 v28, v[48:49] offset:5120
	ds_write_b32 v30, v50 offset:2080
	s_waitcnt lgkmcnt(0)
	s_barrier
; #define MFMA16(a, b, c) __builtin_amdgcn_mfma_f32_16x16x32_bf16((a), (b), (c), 0, 0, 0)
; DI bf16_t f2bf(float x) { return (bf16_t)(pk2(x, 0.f) & 0xffffu); }
; DI float bf2f(unsigned x) { return __uint_as_float(x << 16); }
; DI u32x2 pk4(float a, float b, float c, float d) { u32x2 r; r.x = pk2(a, b); r.y = pk2(c, d); return r; }
;     ...
;     for (int u = vb; u < 256; u += nb) {
;     ...
;             for (int e = 0; e < 2; ++e) {
;                 float z = bb[e];
; #pragma unroll
;                 for (int q = 0; q < 4; ++q) { z += a4[q].x * wa[e][4 * q] + a4[q].y * wa[e][4 * q + 1] + a4[q].z * wa[e][4 * q + 2] + a4[q].w * wa[e][4 * q + 3]; }
;                 cum[e] = (fminf(z, 0.f) - __logf(1.f + __expf(-fabsf(z)))) * (1.f / 16.f);
;             }
; #pragma unroll
;             for (int o = 1; o < 64; o <<= 1) {
;                 const float t0 = __shfl_up(cum[0], o), t1 = __shfl_up(cum[1], o);
;                 if (l >= o) { cum[0] += t0; cum[1] += t1; }
;             }
;             const float tot0 = __shfl(cum[0], 63), tot1 = __shfl(cum[1], 63);
;             kdl[(buf * 16 + 2 * w) * 64 + l] = f2bf(bf2f(kraw & 0xffffu) * __expf(tot0 - cum[0]));
;             kdl[(buf * 16 + 2 * w + 1) * 64 + l] = f2bf(bf2f(kraw >> 16) * __expf(tot1 - cum[1]));
;             if (l == 0) { decl[buf * 16 + 2 * w] = __expf(tot0); decl[buf * 16 + 2 * w + 1] = __expf(tot1); }
;             __syncthreads();
;             const f32x4 d4 = *(const f32x4*)(decl + buf * 16 + (l >> 4) * 4);
; #pragma unroll
;             for (int e = 0; e < 2; ++e) acc[e] = acc[e] * d4;
; #pragma unroll
;             for (int ks = 0; ks < 2; ++ks) {
;                 const bf16x8 af = *(const bf16x8*)(kdl + (buf * 16 + (l & 15)) * 64 + ks * 32 + (l >> 4) * 8);
; #pragma unroll
;                 for (int e = 0; e < 2; ++e) acc[e] = MFMA16(af, vfr[e][ks], acc[e]);
;             }
;             const int cidx = b * 64 + n;
; #pragma unroll
;             for (int e = 0; e < 2; ++e) {
;                 const int vv = (2 * w + e) * 16 + (l & 15);
;                 *(u32x2*)(ST + (((size_t)(cidx * 4 + hh)) * 256 + vv) * 128 + ksl * 16 + (l >> 4) * 4) = pk4(acc[e].x, acc[e].y, acc[e].z, acc[e].w);
;             }
;         }
;     }
	ds_read_b128 v[8:11], v29 offset:5120
	ds_read_b128 v[12:15], v29 offset:5136
	ds_read_b128 v[16:19], v29 offset:5152
	ds_read_b128 v[20:23], v29 offset:5168
	ds_read_b32 v24, v31 offset:2080
	ds_read_b128 v[154:157], v75 offset:0
	ds_read_b128 v[240:243], v164 offset:4096
	ds_read_b128 v[236:239], v75 offset:64
	s_waitcnt lgkmcnt(3)
	v_pk_fma_f32 v[64:65], v[8:9], v[86:87], v[118:119] op_sel:[0,0,0] op_sel_hi:[0,1,1]
	v_pk_mul_f32 v[66:67], v[16:17], v[102:103] op_sel:[0,0] op_sel_hi:[0,1]
	v_pk_fma_f32 v[64:65], v[8:9], v[88:89], v[64:65] op_sel:[1,0,0] op_sel_hi:[1,1,1]
	v_pk_fma_f32 v[66:67], v[16:17], v[104:105], v[66:67] op_sel:[1,0,0] op_sel_hi:[1,1,1]
	v_pk_fma_f32 v[64:65], v[10:11], v[90:91], v[64:65] op_sel:[0,0,0] op_sel_hi:[0,1,1]
	v_pk_fma_f32 v[66:67], v[18:19], v[106:107], v[66:67] op_sel:[0,0,0] op_sel_hi:[0,1,1]
	v_pk_fma_f32 v[64:65], v[10:11], v[92:93], v[64:65] op_sel:[1,0,0] op_sel_hi:[1,1,1]
	v_pk_fma_f32 v[66:67], v[18:19], v[108:109], v[66:67] op_sel:[1,0,0] op_sel_hi:[1,1,1]
	v_pk_fma_f32 v[64:65], v[12:13], v[94:95], v[64:65] op_sel:[0,0,0] op_sel_hi:[0,1,1]
	v_pk_fma_f32 v[66:67], v[20:21], v[110:111], v[66:67] op_sel:[0,0,0] op_sel_hi:[0,1,1]
	v_pk_fma_f32 v[64:65], v[12:13], v[96:97], v[64:65] op_sel:[1,0,0] op_sel_hi:[1,1,1]
	v_pk_fma_f32 v[66:67], v[20:21], v[112:113], v[66:67] op_sel:[1,0,0] op_sel_hi:[1,1,1]
	v_pk_fma_f32 v[64:65], v[14:15], v[98:99], v[64:65] op_sel:[0,0,0] op_sel_hi:[0,1,1]
	v_pk_fma_f32 v[66:67], v[22:23], v[114:115], v[66:67] op_sel:[0,0,0] op_sel_hi:[0,1,1]
	v_pk_fma_f32 v[64:65], v[14:15], v[100:101], v[64:65] op_sel:[1,0,0] op_sel_hi:[1,1,1]
	v_pk_fma_f32 v[66:67], v[22:23], v[116:117], v[66:67] op_sel:[1,0,0] op_sel_hi:[1,1,1]
	v_lshlrev_b32_e32 v148, 16, v24
	v_pk_add_f32 v[64:65], v[64:65], v[66:67]
	v_and_b32_e32 v149, 0xffff0000, v24
	s_waitcnt lgkmcnt(0)
	v_pk_mul_f32 v[0:1], v[0:1], v[240:241]
	v_pk_mul_f32 v[2:3], v[2:3], v[242:243]
	v_pk_mul_f32 v[4:5], v[4:5], v[240:241]
	v_pk_mul_f32 v[6:7], v[6:7], v[242:243]
	s_waitcnt vmcnt(8)
	s_nop 0
	v_mfma_f32_16x16x32_bf16 v[0:3], v[154:157], v[194:197], v[0:3]
	v_mfma_f32_16x16x32_bf16 v[4:7], v[154:157], v[202:205], v[4:7]
	v_mfma_f32_16x16x32_bf16 v[0:3], v[236:239], v[198:201], v[0:3]
	v_mfma_f32_16x16x32_bf16 v[4:7], v[236:239], v[206:209], v[4:7]
	v_mul_f32_e64 v68, |v64|, v220
	v_mul_f32_e64 v69, |v65|, v220
	v_exp_f32_e32 v68, v68
	v_exp_f32_e32 v69, v69
	v_min_f32_e32 v70, 0, v64
	v_min_f32_e32 v71, 0, v65
	v_pk_add_f32 v[68:69], v[68:69], v[222:223]
	s_nop 0
	v_log_f32_e32 v138, v68
	v_log_f32_e32 v139, v69
	s_nop 0
	v_pk_mul_f32 v[140:141], v[138:139], v[224:225]
	s_nop 0
	v_pk_fma_f32 v[142:143], v[138:139], v[224:225], v[140:141] neg_lo:[0,0,1] neg_hi:[0,0,1]
	s_nop 0
	v_pk_fma_f32 v[142:143], v[138:139], v[226:227], v[142:143]
	s_nop 0
	v_pk_fma_f32 v[142:143], v[138:139], v[224:225], v[142:143]
	s_nop 0
	v_pk_add_f32 v[144:145], v[70:71], v[142:143] neg_lo:[0,1] neg_hi:[0,1]
	s_nop 0
	v_pk_mul_f32 v[144:145], v[144:145], v[214:215]
	v_cvt_pk_bf16_f32 v244, v0, v1
	v_cvt_pk_bf16_f32 v245, v2, v3
	v_cvt_pk_bf16_f32 v246, v4, v5
	v_cvt_pk_bf16_f32 v247, v6, v7
	global_store_dwordx2 v234, v[244:245], s[100:101]
	global_store_dwordx2 v235, v[246:247], s[100:101]
	s_add_u32 s100, s100, 0x40000
	s_addc_u32 s101, s101, 0
	v_add_f32_dpp v144, v144, v144 row_shr:1 row_mask:0xf bank_mask:0xf
	v_add_f32_dpp v145, v145, v145 row_shr:1 row_mask:0xf bank_mask:0xf
	s_nop 0
	v_add_f32_dpp v144, v144, v144 row_shr:2 row_mask:0xf bank_mask:0xf
	v_add_f32_dpp v145, v145, v145 row_shr:2 row_mask:0xf bank_mask:0xf
	s_nop 0
	v_add_f32_dpp v144, v144, v144 row_shr:4 row_mask:0xf bank_mask:0xf
	v_add_f32_dpp v145, v145, v145 row_shr:4 row_mask:0xf bank_mask:0xf
	s_nop 0
	v_add_f32_dpp v144, v144, v144 row_shr:8 row_mask:0xf bank_mask:0xf
	v_add_f32_dpp v145, v145, v145 row_shr:8 row_mask:0xf bank_mask:0xf
	s_nop 0
	v_add_f32_dpp v144, v144, v144 row_bcast:15 row_mask:0xa bank_mask:0xf
	v_add_f32_dpp v145, v145, v145 row_bcast:15 row_mask:0xa bank_mask:0xf
	s_nop 0
	v_add_f32_dpp v144, v144, v144 row_bcast:31 row_mask:0xc bank_mask:0xf
	v_add_f32_dpp v145, v145, v145 row_bcast:31 row_mask:0xc bank_mask:0xf
	s_nop 0
	v_readlane_b32 s98, v144, 63
	v_readlane_b32 s99, v145, 63
	s_nop 1
	v_pk_add_f32 v[146:147], s[98:99], v[144:145] neg_lo:[0,1] neg_hi:[0,1]
	v_mul_f32_e64 v152, s98, v228
	v_mul_f32_e64 v153, s99, v228
	v_pk_mul_f32 v[146:147], v[146:147], v[228:229]
	v_exp_f32_e32 v152, v152
	v_exp_f32_e32 v153, v153
	v_exp_f32_e32 v146, v146
	v_exp_f32_e32 v147, v147
	s_nop 0
	v_pk_mul_f32 v[146:147], v[146:147], v[148:149]
	s_nop 0
	v_cvt_pk_bf16_f32 v150, v146, v147
	s_nop 0
	ds_write_b16 v172, v150 offset:2048
	ds_write_b16_d16_hi v172, v150 offset:2176
	s_and_saveexec_b64 s[20:21], vcc
	ds_write_b64 v163, v[152:153] offset:4160
	s_mov_b64 exec, s[20:21]
	s_waitcnt lgkmcnt(0)
	s_barrier
	ds_read_b128 v[154:157], v75 offset:2048
	ds_read_b128 v[240:243], v164 offset:4160
	ds_read_b128 v[236:239], v75 offset:2112
	s_waitcnt lgkmcnt(0)
	v_pk_mul_f32 v[0:1], v[0:1], v[240:241]
	v_pk_mul_f32 v[2:3], v[2:3], v[242:243]
	v_pk_mul_f32 v[4:5], v[4:5], v[240:241]
	v_pk_mul_f32 v[6:7], v[6:7], v[242:243]
	s_waitcnt vmcnt(4)
	s_nop 0
	v_mfma_f32_16x16x32_bf16 v[0:3], v[154:157], v[32:35], v[0:3]
	v_mfma_f32_16x16x32_bf16 v[4:7], v[154:157], v[40:43], v[4:7]
	v_mfma_f32_16x16x32_bf16 v[0:3], v[236:239], v[36:39], v[0:3]
	v_mfma_f32_16x16x32_bf16 v[4:7], v[236:239], v[44:47], v[4:7]
	s_nop 7
	s_nop 1
	v_cvt_pk_bf16_f32 v244, v0, v1
	v_cvt_pk_bf16_f32 v245, v2, v3
	v_cvt_pk_bf16_f32 v246, v4, v5
	v_cvt_pk_bf16_f32 v247, v6, v7
	global_store_dwordx2 v234, v[244:245], s[100:101]
	global_store_dwordx2 v235, v[246:247], s[100:101]
	s_add_u32 s100, s100, 0x40000
	s_addc_u32 s101, s101, 0
	s_add_i32 s56, s56, s96
	s_cmpk_gt_i32 s56, 0xff
	s_cbranch_scc0 .LBB0_418
